# GEMM tile headers without the epilogue-store drains; RWKV stage without dead c1/c2 reductions; barrier leader reads invalidate counter with write-back wait
# baseline (speedup 1.0000x reference)
; __device__ __forceinline__ unsigned xb_ld(unsigned* p)              { return __hip_atomic_load(p, __ATOMIC_RELAXED, __HIP_MEMORY_SCOPE_AGENT); }
; __device__ __forceinline__ unsigned xb_add(unsigned* p, unsigned v) { return __hip_atomic_fetch_add(p, v, __ATOMIC_RELAXED, __HIP_MEMORY_SCOPE_AGENT); }
; #define XB_SPIN(cond, bar) do { unsigned _sp = 0; while (cond) { __builtin_amdgcn_s_sleep(1); \
;     if ((++_sp & 255u) == 0u) { if (xb_ld(&(bar)[XB_TMO])) break; if (_sp > XB_SPIN_CAP) { atomicAdd(&(bar)[XB_TMO], 1u); break; } } } } while (0)
; __device__ __forceinline__ void xcd_barrier(const XcdBarrier& b) {
;     ...
;     const unsigned old = xb_add(&bar[XB_XSUB(b.x)], 1u);
;     const unsigned gen = old / nloc;
;     if (old + 1u == (gen + 1u) * nloc) {
;       __builtin_amdgcn_fence(__ATOMIC_RELEASE, "agent");
;       asm volatile("s_waitcnt vmcnt(0)" ::: "memory");
;       const unsigned og = xb_add(&bar[XB_TOP], 1u);
;       const unsigned tg = og / nx;
;       if (og + 1u == (tg + 1u) * nx) xb_add(&bar[XB_TOPGEN], 1u);
;       else XB_SPIN(xb_ld(&bar[XB_TOPGEN]) == tg, bar);
.LBB0_46:
	s_andn2_saveexec_b64 s[10:11], s[10:11]
	s_cbranch_execz .LBB0_64
	v_mov_b32_e32 v5, v1
	v_sub_u32_e32 v6, v2, v1
	v_add_u32_e32 v6, -1, v6
	s_mov_b64 s[10:11], exec
	buffer_wbl2 sc1
	global_load_dword v7, v198, s[8:9] offset:1152 sc1
	s_waitcnt lgkmcnt(0)
	s_waitcnt vmcnt(0)
	s_mov_b32 s4, 0
	v_cmp_eq_u32_e32 vcc, v7, v6
	s_nop 1
	s_cbranch_vccnz .Lxb_idone

; __device__ __forceinline__ void rwkv_scan_job(const P& p, int job, char* smc) {
;     ...
;     float kkr[4], kpr[4], rs[4], vs[4], ss = 0.f;
; #pragma unroll
;     for (int i = 0; i < 4; i++) {
;       rs[i] = r[i] + (rp[i] - r[i]) * mur[i];
;       float ks = k[i] + (kpv[i] - k[i]) * muk[i];
;       vs[i] = v[i] + (vp[i] - v[i]) * muv[i];
;       kkr[i] = ks * kkc[i];
;       ss += kkr[i] * kkr[i];
;       kpr[i] = ks * (1.f + (a[i] - 1.f) * kac[i]);
;     }
;     ss = sum16(ss);
;     const float inv = rsqrtf(fmaxf(ss, 1e-24f));
;     float c1 = 0.f, c2 = 0.f, c3 = 0.f;
;     float dk[4], kk4[4], kka4[4], wr4[4];
; #pragma unroll
;     for (int i = 0; i < 4; i++) {
;       kk4[i] = kkr[i] * inv;
;       kka4[i] = kk4[i] * a[i];
;       dk[i] = __expf(ld[i]);
;       wr4[i] = dk[i] * rs[i];
;       c1 += kka4[i] * rs[i];
;       c2 += kpr[i] * rs[i];
;       c3 += kpr[i] * rs[i] * rkc[i];
;     }
;     c1 = sum16(c1); c2 = sum16(c2); c3 = sum16(c3);
;     *(float4*)&bf.dec[tl][jg * 4] = make_float4(dk[0], dk[1], dk[2], dk[3]);
;     *(float4*)&bf.kk[tl][jg * 4] = make_float4(kk4[0], kk4[1], kk4[2], kk4[3]);
;     *(float4*)&bf.kka[tl][jg * 4] = make_float4(kka4[0], kka4[1], kka4[2], kka4[3]);
;     *(float4*)&bf.kp[tl][jg * 4] = make_float4(kpr[0], kpr[1], kpr[2], kpr[3]);
;     *(float4*)&bf.wr[tl][jg * 4] = make_float4(wr4[0], wr4[1], wr4[2], wr4[3]);
;     if ((jg >> 2) == rq) *(float4*)&bf.v[tl][(jg & 3) * 4] = make_float4(vs[0], vs[1], vs[2], vs[3]);
;     if (jg == 0) { bf.c[tl][0] = c1; bf.c[tl][1] = c2; if (rq == 0) p.c3buf[(size_t)g_t * 8 + h] = c3; }
.LBB0_167:
	s_or_b64 exec, exec, s[6:7]
	v_lshlrev_b32_e32 v60, 16, v79
	v_lshlrev_b32_e32 v58, 16, v78
	v_and_b32_e32 v59, 0xffff0000, v78
	v_and_b32_e32 v66, 0xffff0000, v79
	s_waitcnt vmcnt(0)
	v_lshlrev_b32_e32 v68, 16, v92
	v_sub_f32_e32 v52, v52, v60
	v_and_b32_e32 v70, 0xffff0000, v92
	v_add_f32_e32 v69, -1.0, v68
	v_mul_f32_e32 v104, v14, v52
	v_sub_f32_e32 v52, v53, v66
	v_pk_add_f32 v[50:51], v[50:51], v[58:59] neg_lo:[0,1] neg_hi:[0,1]
	v_lshlrev_b32_e32 v61, 16, v93
	v_and_b32_e32 v67, 0xffff0000, v93
	v_fma_f32 v73, v8, v69, 1.0
	v_add_f32_e32 v69, -1.0, v70
	v_mul_f32_e32 v138, v15, v52
	v_pk_fma_f32 v[50:51], v[12:13], v[50:51], v[58:59]
	v_mov_b32_e32 v105, v139
	v_fma_f32 v75, v9, v69, 1.0
	v_pk_add_f32 v[106:107], v[138:139], v[66:67]
	v_pk_mul_f32 v[58:59], v[20:21], v[50:51]
	v_mov_b32_e32 v69, v50
	v_mov_b32_e32 v71, v51
	v_pk_add_f32 v[50:51], v[104:105], v[60:61]
	v_pk_mul_f32 v[108:109], v[10:11], v[106:107]
	v_pk_mul_f32 v[104:105], v[22:23], v[50:51]
	v_pk_mul_f32 v[110:111], v[58:59], v[58:59]
	v_mov_b32_e32 v120, v108
	v_mov_b32_e32 v121, v104
	v_pk_mul_f32 v[120:121], v[120:121], v[120:121]
	v_add_f32_e32 v60, v110, v111
	v_add_f32_e32 v60, v121, v60
	v_add_f32_e32 v60, v120, v60
	v_lshlrev_b32_e32 v54, 16, v90
	v_and_b32_e32 v55, 0xffff0000, v90
	v_add_f32_dpp v60, v60, v60 quad_perm:[1,0,3,2] row_mask:0xf bank_mask:0xf bound_ctrl:1
	v_mul_f32_e32 v52, 0x3fb8aa3b, v54
	v_lshlrev_b32_e32 v56, 16, v91
	v_add_f32_dpp v60, v60, v60 quad_perm:[2,3,0,1] row_mask:0xf bank_mask:0xf bound_ctrl:1
	v_exp_f32_e32 v54, v52
	v_mul_f32_e32 v52, 0x3fb8aa3b, v55
	v_add_f32_dpp v60, v60, v60 row_half_mirror row_mask:0xf bank_mask:0xf bound_ctrl:1
	s_and_b32 s4, s62, 1
	v_and_b32_e32 v57, 0xffff0000, v91
	v_add_f32_dpp v60, v60, v60 row_mirror row_mask:0xf bank_mask:0xf bound_ctrl:1
	v_max_f32_e32 v60, 0x179abe15, v60
	v_rsq_f32_e32 v140, v60
	v_exp_f32_e32 v55, v52
	v_mul_f32_e32 v52, 0x3fb8aa3b, v56
	s_mov_b32 s7, 1.0
	v_pk_mul_f32 v[58:59], v[58:59], v[140:141] op_sel_hi:[1,0]
	v_exp_f32_e32 v56, v52
	v_mov_b32_e32 v72, v58
	v_mov_b32_e32 v74, v59
	v_mul_f32_e32 v52, 0x3fb8aa3b, v57
	s_mulk_i32 s4, 0x5480
	v_mov_b32_e32 v122, v61
	v_mov_b32_e32 v123, v50
	v_pk_mul_f32 v[68:69], v[72:73], v[68:69]
	v_pk_mul_f32 v[70:71], v[74:75], v[70:71]
	v_pk_mul_f32 v[60:61], v[104:105], v[140:141]
	v_pk_fma_f32 v[50:51], v[22:23], v[50:51], s[6:7]
	v_pk_mul_f32 v[72:73], v[108:109], v[140:141]
	v_pk_fma_f32 v[74:75], v[10:11], v[106:107], s[6:7]
	v_exp_f32_e32 v57, v52
	v_pk_mov_b32 v[66:67], v[66:67], v[106:107] op_sel:[1,0]
	v_add_u32_e32 v52, s4, v114
	v_mov_b32_e32 v61, v51
	v_mov_b32_e32 v73, v75
	v_lshlrev_b32_e32 v62, 16, v76
	v_and_b32_e32 v63, 0xffff0000, v76
	v_lshl_add_u32 v53, v113, 2, v52
	v_pk_mul_f32 v[50:51], v[60:61], v[122:123]
	v_pk_mul_f32 v[66:67], v[72:73], v[66:67]
	v_mov_b32_e32 v61, v72
	ds_write_b128 v53, v[58:61] offset:4096
	v_mov_b32_e32 v58, v68
	v_mov_b32_e32 v59, v70
	v_mov_b32_e32 v60, v50
	v_mov_b32_e32 v61, v66
	v_pk_add_f32 v[42:43], v[42:43], v[62:63] neg_lo:[0,1] neg_hi:[0,1]
	v_lshlrev_b32_e32 v64, 16, v77
	v_and_b32_e32 v65, 0xffff0000, v77
	ds_write_b128 v53, v[58:61] offset:8192
	v_mov_b32_e32 v58, v69
	v_mov_b32_e32 v59, v71
	v_mov_b32_e32 v60, v51
	v_mov_b32_e32 v61, v67
	v_pk_fma_f32 v[42:43], v[0:1], v[42:43], v[62:63]
	ds_write_b128 v53, v[58:61] offset:12288
	v_pk_mul_f32 v[58:59], v[42:43], v[68:69] op_sel_hi:[0,1]
	v_pk_add_f32 v[40:41], v[40:41], v[64:65] neg_lo:[0,1] neg_hi:[0,1]
	ds_write_b128 v53, v[54:57]
	v_mov_b32_e32 v54, v42
	v_mov_b32_e32 v55, v43
	v_fma_f32 v62, v16, v59, 0
	v_pk_mul_f32 v[58:59], v[42:43], v[70:71]
	v_pk_fma_f32 v[40:41], v[2:3], v[40:41], v[64:65]
	v_fmac_f32_e32 v62, v17, v59
	v_mov_b32_e32 v56, v40
	v_mov_b32_e32 v57, v41
	v_mul_f32_e32 v58, v40, v51
	v_mul_f32_e32 v59, v41, v67
	v_fmac_f32_e32 v62, v18, v58
	v_fmac_f32_e32 v62, v19, v59
	s_nop 1
	v_add_f32_dpp v50, v62, v62 quad_perm:[1,0,3,2] row_mask:0xf bank_mask:0xf bound_ctrl:1
	ds_write_b128 v53, v[54:57] offset:16384
	s_nop 1
	v_add_f32_dpp v50, v50, v50 quad_perm:[2,3,0,1] row_mask:0xf bank_mask:0xf bound_ctrl:1
	s_nop 0
	s_nop 1
	v_add_f32_dpp v50, v50, v50 row_half_mirror row_mask:0xf bank_mask:0xf bound_ctrl:1
	s_nop 0
	s_nop 1
	v_mov_b32_dpp v51, v50 row_mirror row_mask:0xf bank_mask:0xf bound_ctrl:1
	s_and_saveexec_b64 s[6:7], s[92:93]
	s_cbranch_execz .LBB0_169
	v_lshlrev_b32_e32 v54, 16, v82
	v_and_b32_e32 v55, 0xffff0000, v82
	v_lshlrev_b32_e32 v56, 16, v83
	v_and_b32_e32 v57, 0xffff0000, v83
	v_pk_add_f32 v[38:39], v[38:39], v[56:57] neg_lo:[0,1] neg_hi:[0,1]
	v_pk_add_f32 v[36:37], v[36:37], v[54:55] neg_lo:[0,1] neg_hi:[0,1]
	v_add3_u32 v53, v52, v115, v116
	v_pk_fma_f32 v[36:37], v[4:5], v[36:37], v[54:55]
	v_pk_fma_f32 v[38:39], v[6:7], v[38:39], v[56:57]
	ds_write_b128 v53, v[36:39] offset:20480
.LBB0_169:
	s_or_b64 exec, exec, s[6:7]
	v_readlane_b32 s68, v229, 51
	v_readlane_b32 s69, v229, 52
	s_and_saveexec_b64 s[6:7], s[68:69]
	s_cbranch_execz .LBB0_160
	v_readlane_b32 s68, v229, 53
	v_readlane_b32 s69, v229, 54
	s_andn2_b64 vcc, exec, s[68:69]
	s_cbranch_vccnz .LBB0_160
	v_readlane_b32 s68, v229, 47
	v_lshlrev_b64 v[36:37], 5, v[84:85]
	v_readlane_b32 s69, v229, 48
	v_add_f32_e32 v38, v50, v51
	s_nop 0
	v_lshl_add_u64 v[36:37], s[68:69], 0, v[36:37]
	global_store_dword v[36:37], v38, off
	s_branch .LBB0_160

; __device__ __forceinline__ int ltid() { int t = threadIdx.x; asm volatile("" : "+v"(t)); return t; }
; #define WAIT_V(n) asm volatile("s_waitcnt vmcnt(%0)" ::"n"(n) : "memory")
; template <class F>
; __device__ __forceinline__ void gemm_big(const ALbf& al, const u16* __restrict__ Wt, int K, int m0, int n0, const F& f, u16* sm) {
;   const int tid = ltid(), lane = tid & 63, wave = tid >> 6;
;   const int wm = wave >> 1, wn = wave & 1;
;   const int rsw = GSW(lane & 15, lane >> 4);
;   f32x4 acc[4][8];
; #pragma unroll
;   for (int i = 0; i < 4; i++)
; #pragma unroll
;     for (int j = 0; j < 8; j++) acc[i][j] = (f32x4){0.f, 0.f, 0.f, 0.f};
;   const int srow = lane >> 2;
;   const int scol = ((lane & 3) ^ ((0 - (srow >> 2)) & 3)) * 8;
;   const u16* ga = al.A + (size_t)(m0 + wave * 16 + srow) * al.lda + scol;
;   const u16* gw = Wt + (size_t)(n0 + wave * 16 + srow) * K + scol;
;   const size_t a64 = (size_t)64 * al.lda, w64 = (size_t)64 * K;
;   const int nk = K >> 5;
;   WAIT_V(0);
;   gb_issue(ga, gw, a64, w64, 0, sm, wave);
.LBB0_194:
	v_mov_b32_e32 v138, v132
	s_lshl_b32 s8, s13, 8
	v_lshrrev_b32_e32 v0, 2, v138
	v_bfe_u32 v140, v138, 4, 2
	v_sub_u32_e32 v0, 0, v0
	v_bitop3_b32 v0, v140, v0, 3 bitop3:0x78
	v_lshlrev_b32_e32 v6, 4, v0
	v_lshrrev_b32_e32 v0, 4, v138
	v_ashrrev_i32_e32 v4, 6, v138
	v_sub_u32_e32 v8, 0, v0
	s_and_b32 s15, s8, 0x3f00
	s_lshl_b32 s8, s13, 1
	v_bfe_u32 v7, v138, 2, 4
	v_xor_b32_e32 v2, v138, v8
	v_lshlrev_b32_e32 v9, 4, v4
	s_load_dwordx16 s[60:75], s[0:1], 0x1a0
	s_and_b32 s14, s8, 0xffffff80
	v_or_b32_e32 v3, v7, v9
	v_lshlrev_b32_e32 v2, 4, v2
	v_add_u32_e32 v0, s15, v3
	v_and_b32_e32 v134, 48, v2
	v_add_u32_e32 v2, s14, v3
	v_ashrrev_i32_e32 v1, 31, v0
	v_ashrrev_i32_e32 v3, 31, v2
	v_lshlrev_b64 v[0:1], 11, v[0:1]
	v_lshlrev_b64 v[2:3], 11, v[2:3]
	v_lshl_add_u64 v[0:1], s[30:31], 0, v[0:1]
	s_waitcnt lgkmcnt(0)
	v_lshl_add_u64 v[2:3], s[68:69], 0, v[2:3]
	v_lshl_add_u64 v[0:1], v[0:1], 0, v[134:135]
	v_lshl_add_u64 v[2:3], v[2:3], 0, v[134:135]
	v_lshlrev_b32_e32 v134, 10, v4
	v_add_u32_e32 v10, 0x1000, v134
	v_readfirstlane_b32 s8, v134
	s_nop 0
	s_mov_b32 m0, s8
	v_readfirstlane_b32 s8, v10
	v_add_u32_e32 v10, 0x2000, v134
	v_lshl_add_u64 v[4:5], v[0:1], 0, s[96:97]
	s_mov_b32 m0, s8
	v_readfirstlane_b32 s8, v10
	v_lshl_add_u64 v[4:5], v[0:1], 0, s[86:87]
	s_mov_b32 m0, s8
	s_mov_b64 s[8:9], 0x60000
	v_add_u32_e32 v10, 0x3000, v134
	v_lshl_add_u64 v[4:5], v[0:1], 0, s[8:9]
	v_readfirstlane_b32 s8, v10
	s_mov_b32 m0, s8
	v_add_u32_e32 v10, 0x5000, v134
	v_add_u32_e32 v4, 0x4000, v134
	s_mov_b64 s[10:11], 0x20040
	v_readfirstlane_b32 s8, v4
	s_mov_b32 m0, s8
	v_readfirstlane_b32 s8, v10
	v_add_u32_e32 v10, 0x6000, v134
	v_lshl_add_u64 v[4:5], v[2:3], 0, s[96:97]
	s_mov_b32 m0, s8
	v_readfirstlane_b32 s8, v10
	v_add_u32_e32 v10, 0x7000, v134
	v_lshl_add_u64 v[4:5], v[0:1], 0, 64
	s_mov_b32 m0, s8
	v_readfirstlane_b32 s8, v10
	v_lshl_add_u64 v[4:5], v[0:1], 0, s[10:11]
	s_mov_b32 m0, s8
	s_mov_b64 s[8:9], 0x40040
	v_add_u32_e32 v10, 0x8000, v134
	v_lshl_add_u64 v[4:5], v[0:1], 0, s[8:9]
	v_readfirstlane_b32 s8, v10
	s_mov_b32 m0, s8
	s_mov_b64 s[8:9], 0x60040
	v_add_u32_e32 v4, 0x9000, v134
	v_lshl_add_u64 v[0:1], v[0:1], 0, s[8:9]
	v_readfirstlane_b32 s8, v4
	v_add_u32_e32 v4, 0xa000, v134
	s_mov_b32 m0, s8
	v_readfirstlane_b32 s8, v4
	v_lshl_add_u64 v[0:1], v[2:3], 0, 64
	s_mov_b32 m0, s8
	s_and_b32 s6, s4, 0xffffff80
	v_lshl_add_u64 v[0:1], v[2:3], 0, s[10:11]
	v_add_u32_e32 v2, 0xb000, v134
	s_and_b32 s7, s12, 0x3f00
	v_readfirstlane_b32 s8, v2
	s_mov_b32 m0, s8
	v_bitop3_b32 v2, v138, 3, v8 bitop3:0x48
	v_lshlrev_b32_e32 v0, 6, v138
	v_and_or_b32 v143, v0, s80, v6
	v_lshlrev_b32_e32 v0, 1, v138
	v_and_b32_e32 v1, 0x43, v138
	v_and_or_b32 v0, v0, 24, v1
	v_lshrrev_b32_e32 v1, 1, v138
	v_and_b32_e32 v1, 2, v1
	v_sub_u32_e32 v1, 0, v1
	v_bitop3_b32 v1, v1, v140, 2 bitop3:0x6c
	v_lshlrev_b32_e32 v1, 4, v1
	v_lshl_or_b32 v144, v0, 6, v1
	v_or_b32_e32 v0, 4, v0
	v_lshlrev_b32_e32 v1, 6, v0
	v_lshrrev_b32_e32 v0, 2, v0
	v_sub_u32_e32 v0, 0, v0
	v_bitop3_b32 v0, v0, v140, 3 bitop3:0x6c
	v_lshl_or_b32 v145, v0, 4, v1
	v_or_b32_e32 v0, s6, v7
	v_add_u32_e32 v0, v0, v9
	v_ashrrev_i32_e32 v1, 31, v0
	v_lshlrev_b64 v[0:1], 11, v[0:1]
	v_lshlrev_b32_e32 v2, 4, v2
	v_or_b32_e32 v0, v0, v2
	v_lshl_add_u64 v[128:129], s[68:69], 0, v[0:1]
	v_or_b32_e32 v0, s7, v7
	v_add_u32_e32 v0, v0, v9
	v_ashrrev_i32_e32 v1, 31, v0
	s_nop 0
	v_lshlrev_b64 v[0:1], 11, v[0:1]
	s_waitcnt lgkmcnt(0)
; #define WAIT_V(n) asm volatile("s_waitcnt vmcnt(%0)" ::"n"(n) : "memory")
; #define RAW_BARRIER() do { asm volatile("s_waitcnt lgkmcnt(0)" ::: "memory"); __builtin_amdgcn_s_barrier(); } while (0)
; #define DSR(dst, addr, off) asm volatile("ds_read_b128 %0, %1 offset:%2" : "=v"(dst) : "v"(addr), "n"(off) : "memory")
; __device__ __forceinline__ void gb_step(const u16* ga, const u16* gw, size_t a64, size_t w64, int ko, bool issue, ...
;     ...
;   const unsigned rdb = (unsigned)(size_t)(__attribute__((address_space(3))) const char*)rd;
;   const unsigned ab = rdb + (unsigned)(((wm * 128 + (lane & 15)) * GST + rsw) * 2);
;   const int wr0 = wn * 64 + (((lane & 15) >> 2) << 3) + (lane & 3);
;   const unsigned bb0 = rdb + (unsigned)((256 * GST + wr0 * GST + GSW(wr0, lane >> 4)) * 2);
;   const unsigned bb1 = rdb + (unsigned)((256 * GST + (wr0 + 4) * GST + GSW(wr0 + 4, lane >> 4)) * 2);
;   bf16x8 wf0, wf1, wf2, wf3, xf0, xf1, xf2, xf3, xf4, xf5, xf6, xf7;
;     ...
;   DSR(wf0, bb0, 0); DSR(wf1, bb1, 0); DSR(wf2, bb0, 2048); DSR(wf3, bb1, 2048);
;   DSR(xf0, ab, 0); DSR(xf1, ab, 1024); DSR(xf2, ab, 2048); DSR(xf3, ab, 3072);
;   DSR(xf4, ab, 4096); DSR(xf5, ab, 5120); DSR(xf6, ab, 6144); DSR(xf7, ab, 7168);
; template <class F>
; __device__ __forceinline__ void gemm_big(const ALbf& al, const u16* __restrict__ Wt, int K, int m0, int n0, const F& f, u16* sm) {
;     ...
;   f32x4 acc[4][8];
; #pragma unroll
;   for (int i = 0; i < 4; i++)
; #pragma unroll
;     for (int j = 0; j < 8; j++) acc[i][j] = (f32x4){0.f, 0.f, 0.f, 0.f};
;   const int srow = lane >> 2;
;   const int scol = ((lane & 3) ^ ((0 - (srow >> 2)) & 3)) * 8;
;   const u16* ga = al.A + (size_t)(m0 + wave * 16 + srow) * al.lda + scol;
;   const u16* gw = Wt + (size_t)(n0 + wave * 16 + srow) * K + scol;
;   const size_t a64 = (size_t)64 * al.lda, w64 = (size_t)64 * K;
;   const int nk = K >> 5;
;   WAIT_V(0);
;   gb_issue(ga, gw, a64, w64, 0, sm, wave);
;   gb_issue(ga, gw, a64, w64, 32, sm + GB_STAGE_EL, wave);
;   WAIT_V(6);
;   RAW_BARRIER();
	v_or_b32_e32 v0, v0, v2
	v_lshl_add_u64 v[130:131], s[30:31], 0, v[0:1]
	v_mov_b32_e32 v0, 0
	s_mov_b32 s16, 0
	s_mov_b64 s[6:7], 0
	s_mov_b32 s17, 0
	v_mov_b32_e32 v1, v0
	v_mov_b32_e32 v2, v0
	v_mov_b32_e32 v3, v0
	v_mov_b32_e32 v4, v0
	v_mov_b32_e32 v5, v0
	v_mov_b32_e32 v6, v0
	v_mov_b32_e32 v7, v0
	v_mov_b32_e32 v32, v0
	v_mov_b32_e32 v33, v0
	v_mov_b32_e32 v34, v0
	v_mov_b32_e32 v35, v0
	v_mov_b32_e32 v36, v0
	v_mov_b32_e32 v37, v0
	v_mov_b32_e32 v38, v0
	v_mov_b32_e32 v39, v0
	v_mov_b32_e32 v8, v0
	v_mov_b32_e32 v9, v0
	v_mov_b32_e32 v10, v0
	v_mov_b32_e32 v11, v0
	v_mov_b32_e32 v12, v0
	v_mov_b32_e32 v13, v0
	v_mov_b32_e32 v14, v0
	v_mov_b32_e32 v15, v0
	v_mov_b32_e32 v48, v0
	v_mov_b32_e32 v49, v0
	v_mov_b32_e32 v50, v0
	v_mov_b32_e32 v51, v0
	v_mov_b32_e32 v52, v0
	v_mov_b32_e32 v53, v0
	v_mov_b32_e32 v54, v0
	v_mov_b32_e32 v55, v0
	v_mov_b32_e32 v16, v0
	v_mov_b32_e32 v17, v0
	v_mov_b32_e32 v18, v0
	v_mov_b32_e32 v19, v0
	v_mov_b32_e32 v20, v0
	v_mov_b32_e32 v21, v0
	v_mov_b32_e32 v22, v0
	v_mov_b32_e32 v23, v0
	v_mov_b32_e32 v64, v0
	v_mov_b32_e32 v65, v0
	v_mov_b32_e32 v66, v0
	v_mov_b32_e32 v67, v0
	v_mov_b32_e32 v68, v0
	v_mov_b32_e32 v69, v0
	v_mov_b32_e32 v70, v0
	v_mov_b32_e32 v71, v0
	v_mov_b32_e32 v24, v0
	v_mov_b32_e32 v25, v0
	v_mov_b32_e32 v26, v0
	v_mov_b32_e32 v27, v0
	v_mov_b32_e32 v28, v0
	v_mov_b32_e32 v29, v0
	v_mov_b32_e32 v30, v0
	v_mov_b32_e32 v31, v0
	v_mov_b32_e32 v80, v0
	v_mov_b32_e32 v81, v0
	v_mov_b32_e32 v82, v0
	v_mov_b32_e32 v83, v0
	v_mov_b32_e32 v84, v0
	v_mov_b32_e32 v85, v0
	v_mov_b32_e32 v86, v0
	v_mov_b32_e32 v87, v0
	v_mov_b32_e32 v40, v0
	v_mov_b32_e32 v41, v0
	v_mov_b32_e32 v42, v0
	v_mov_b32_e32 v43, v0
	v_mov_b32_e32 v44, v0
	v_mov_b32_e32 v45, v0
	v_mov_b32_e32 v46, v0
	v_mov_b32_e32 v47, v0
	v_mov_b32_e32 v96, v0
	v_mov_b32_e32 v97, v0
	v_mov_b32_e32 v98, v0
	v_mov_b32_e32 v99, v0
	v_mov_b32_e32 v100, v0
	v_mov_b32_e32 v101, v0
	v_mov_b32_e32 v102, v0
	v_mov_b32_e32 v103, v0
	v_mov_b32_e32 v56, v0
	v_mov_b32_e32 v57, v0
	v_mov_b32_e32 v58, v0
	v_mov_b32_e32 v59, v0
	v_mov_b32_e32 v60, v0
	v_mov_b32_e32 v61, v0
	v_mov_b32_e32 v62, v0
	v_mov_b32_e32 v63, v0
	v_mov_b32_e32 v104, v0
	v_mov_b32_e32 v105, v0
	v_mov_b32_e32 v106, v0
	v_mov_b32_e32 v107, v0
	v_mov_b32_e32 v108, v0
	v_mov_b32_e32 v109, v0
	v_mov_b32_e32 v110, v0
	v_mov_b32_e32 v111, v0
	v_mov_b32_e32 v72, v0
	v_mov_b32_e32 v73, v0
	v_mov_b32_e32 v74, v0
	v_mov_b32_e32 v75, v0
	v_mov_b32_e32 v76, v0
	v_mov_b32_e32 v77, v0
	v_mov_b32_e32 v78, v0
	v_mov_b32_e32 v79, v0
	v_mov_b32_e32 v112, v0
	v_mov_b32_e32 v113, v0
	v_mov_b32_e32 v114, v0
	v_mov_b32_e32 v115, v0
	v_mov_b32_e32 v116, v0
	v_mov_b32_e32 v117, v0
	v_mov_b32_e32 v118, v0
	v_mov_b32_e32 v119, v0
	v_mov_b32_e32 v88, v0
	v_mov_b32_e32 v89, v0
	v_mov_b32_e32 v90, v0
	v_mov_b32_e32 v91, v0
	v_mov_b32_e32 v92, v0
	v_mov_b32_e32 v93, v0
	v_mov_b32_e32 v94, v0
	v_mov_b32_e32 v95, v0
	v_mov_b32_e32 v120, v0
	v_mov_b32_e32 v121, v0
	v_mov_b32_e32 v122, v0
	v_mov_b32_e32 v123, v0
	v_mov_b32_e32 v124, v0
	v_mov_b32_e32 v125, v0
	v_mov_b32_e32 v126, v0
	v_mov_b32_e32 v127, v0
	v_readfirstlane_b32 s6, v130
	v_readfirstlane_b32 s7, v131
	v_readfirstlane_b32 s8, v128
	v_readfirstlane_b32 s9, v129
	v_readfirstlane_b32 s17, v134
	v_and_b32_e32 v176, 63, v132
	v_lshrrev_b32_e32 v177, 6, v132
	v_lshrrev_b32_e32 v178, 3, v176
	v_and_b32_e32 v179, 7, v176
	v_lshrrev_b32_e32 v180, 4, v176
	v_and_b32_e32 v181, 1, v177
	v_lshrrev_b32_e32 v182, 1, v177
	v_lshl_add_u32 v183, v181, 2, v180
	v_xor_b32_e32 v183, v179, v183
	v_lshl_add_u32 v184, v177, 3, v178
	v_lshlrev_b32_e32 v188, 11, v184
	v_lshl_add_u32 v128, v183, 4, v188
	v_add_u32_e32 v129, 0x10000, v128
	v_add_u32_e32 v130, 0x40000, v128
	v_add_u32_e32 v131, 0x50000, v128
	v_bfe_u32 v185, v178, 1, 1
	v_lshl_or_b32 v185, v181, 1, v185
	v_lshl_or_b32 v185, v182, 2, v185
	v_xor_b32_e32 v185, v179, v185
	v_lshl_add_u32 v134, v185, 4, v188
	v_add_u32_e32 v143, 0x10000, v134
	v_add_u32_e32 v196, 0x20000, v134
	v_add_u32_e32 v197, 0x30000, v134
	v_and_b32_e32 v186, 15, v176
	v_bfe_u32 v187, v176, 1, 3
	v_xor_b32_e32 v187, v180, v187
	v_lshlrev_b32_e32 v187, 4, v187
	v_lshl_add_u32 v188, v182, 6, v186
	v_lshl_add_u32 v219, v188, 7, v187
	v_xor_b32_e32 v228, 64, v219
	v_lshrrev_b32_e32 v189, 2, v186
	v_lshlrev_b32_e32 v189, 3, v189
	v_and_b32_e32 v188, 3, v186
	v_add_u32_e32 v189, v189, v188
	v_lshl_add_u32 v189, v181, 6, v189
	v_lshl_add_u32 v231, v189, 7, v187
	v_xor_b32_e32 v216, 64, v231
	s_lshl_b32 s11, s17, 5
	s_sub_u32 s6, s6, s11
	s_subb_u32 s7, s7, 0
	s_sub_u32 s8, s8, s11
	s_subb_u32 s9, s9, 0
	s_add_u32 m0, s17, 0x8000
	s_nop 0
	global_load_lds_dwordx4 v128, s[6:7]
	s_add_u32 m0, s17, 0x9000
	s_nop 0
	global_load_lds_dwordx4 v129, s[6:7]
	s_add_u32 m0, s17, 0xa000
	s_nop 0
	global_load_lds_dwordx4 v130, s[6:7]
	s_add_u32 m0, s17, 0xb000
	s_nop 0
	global_load_lds_dwordx4 v131, s[6:7]
	s_add_u32 s6, s6, 0x20000
	s_addc_u32 s7, s7, 0
	s_add_u32 m0, s17, 0xc000
	s_nop 0
	global_load_lds_dwordx4 v128, s[6:7]
	s_add_u32 m0, s17, 0xd000
	s_nop 0
	global_load_lds_dwordx4 v129, s[6:7]
	s_add_u32 m0, s17, 0xe000
	s_nop 0
	global_load_lds_dwordx4 v130, s[6:7]
	s_add_u32 m0, s17, 0xf000
	s_nop 0
	global_load_lds_dwordx4 v131, s[6:7]
	s_add_u32 s6, s6, 0xfffe0080
	s_addc_u32 s7, s7, -1
	s_add_u32 m0, s17, 0x0
	s_nop 0
	global_load_lds_dwordx4 v134, s[8:9]
	s_add_u32 m0, s17, 0x1000
	s_nop 0
	global_load_lds_dwordx4 v143, s[8:9]
	s_add_u32 m0, s17, 0x2000
	s_nop 0
	global_load_lds_dwordx4 v196, s[8:9]
	s_add_u32 m0, s17, 0x3000
	s_nop 0
	global_load_lds_dwordx4 v197, s[8:9]
	s_add_u32 s8, s8, 0x80
	s_addc_u32 s9, s9, 0
	s_add_u32 m0, s17, 0x4000
	s_nop 0
	global_load_lds_dwordx4 v134, s[8:9]
	s_add_u32 m0, s17, 0x5000
	s_nop 0
	global_load_lds_dwordx4 v143, s[8:9]
	s_add_u32 m0, s17, 0x6000
	s_nop 0
	global_load_lds_dwordx4 v196, s[8:9]
	s_add_u32 m0, s17, 0x7000
	s_nop 0
	global_load_lds_dwordx4 v197, s[8:9]
	s_add_u32 s8, s8, 0x80
	s_addc_u32 s9, s9, 0
	s_waitcnt vmcnt(0)
	s_barrier
	s_mov_b32 s10, 0
	s_mov_b32 s16, 0
	ds_read_b128 v[144:147], v219 offset:32768
	ds_read_b128 v[148:151], v219 offset:34816
	ds_read_b128 v[152:155], v219 offset:36864
	ds_read_b128 v[156:159], v219 offset:38912
	ds_read_b128 v[160:163], v228 offset:32768
	ds_read_b128 v[164:167], v228 offset:34816
	ds_read_b128 v[168:171], v228 offset:36864
	ds_read_b128 v[172:175], v228 offset:38912
	v_add_u32_e32 v248, s10, v231
	ds_read_b128 v[236:239], v248 offset:0
	ds_read_b128 v[240:243], v248 offset:512
	ds_read_b128 v[244:247], v248 offset:4096
	ds_read_b128 v[248:251], v248 offset:4608
	s_waitcnt lgkmcnt(0)
	s_barrier

; __device__ __forceinline__ int ltid() { int t = threadIdx.x; asm volatile("" : "+v"(t)); return t; }
; #define WAIT_V(n) asm volatile("s_waitcnt vmcnt(%0)" ::"n"(n) : "memory")
; template <class F>
; __device__ __forceinline__ void gemm_big(const ALbf& al, const u16* __restrict__ Wt, int K, int m0, int n0, const F& f, u16* sm) {
;   const int tid = ltid(), lane = tid & 63, wave = tid >> 6;
;   const int wm = wave >> 1, wn = wave & 1;
;   const int rsw = GSW(lane & 15, lane >> 4);
;   f32x4 acc[4][8];
; #pragma unroll
;   for (int i = 0; i < 4; i++)
; #pragma unroll
;     for (int j = 0; j < 8; j++) acc[i][j] = (f32x4){0.f, 0.f, 0.f, 0.f};
;   const int srow = lane >> 2;
;   const int scol = ((lane & 3) ^ ((0 - (srow >> 2)) & 3)) * 8;
;   const u16* ga = al.A + (size_t)(m0 + wave * 16 + srow) * al.lda + scol;
;   const u16* gw = Wt + (size_t)(n0 + wave * 16 + srow) * K + scol;
;   const size_t a64 = (size_t)64 * al.lda, w64 = (size_t)64 * K;
;   const int nk = K >> 5;
;   WAIT_V(0);
;   gb_issue(ga, gw, a64, w64, 0, sm, wave);
.LBB0_218:
	v_mov_b32_e32 v138, v132
	s_lshl_b32 s12, s17, 8
	v_lshrrev_b32_e32 v0, 2, v138
	v_bfe_u32 v140, v138, 4, 2
	v_sub_u32_e32 v0, 0, v0
	v_bitop3_b32 v0, v140, v0, 3 bitop3:0x78
	v_lshlrev_b32_e32 v6, 4, v0
	v_lshrrev_b32_e32 v0, 4, v138
	v_ashrrev_i32_e32 v4, 6, v138
	v_sub_u32_e32 v8, 0, v0
	s_and_b32 s61, s12, 0x3f00
	s_lshl_b32 s12, s17, 1
	v_bfe_u32 v7, v138, 2, 4
	v_xor_b32_e32 v2, v138, v8
	v_lshlrev_b32_e32 v9, 4, v4
	s_load_dwordx16 s[64:79], s[0:1], 0x160
	s_and_b32 s60, s12, 0xffffff80
	v_or_b32_e32 v3, v7, v9
	v_lshlrev_b32_e32 v2, 4, v2
	v_add_u32_e32 v0, s61, v3
	v_and_b32_e32 v134, 48, v2
	v_add_u32_e32 v2, s60, v3
	v_ashrrev_i32_e32 v1, 31, v0
	v_ashrrev_i32_e32 v3, 31, v2
	v_lshlrev_b64 v[0:1], 11, v[0:1]
	v_lshlrev_b64 v[2:3], 11, v[2:3]
	s_waitcnt lgkmcnt(0)
	v_lshl_add_u64 v[0:1], s[30:31], 0, v[0:1]
	v_lshl_add_u64 v[2:3], s[74:75], 0, v[2:3]
	v_lshl_add_u64 v[0:1], v[0:1], 0, v[134:135]
	v_lshl_add_u64 v[2:3], v[2:3], 0, v[134:135]
	v_lshlrev_b32_e32 v134, 10, v4
	v_add_u32_e32 v10, 0x1000, v134
	v_readfirstlane_b32 s12, v134
	s_nop 0
	s_mov_b32 m0, s12
	v_readfirstlane_b32 s12, v10
	v_add_u32_e32 v10, 0x2000, v134
	v_lshl_add_u64 v[4:5], v[0:1], 0, s[96:97]
	s_mov_b32 m0, s12
	v_readfirstlane_b32 s12, v10
	v_lshl_add_u64 v[4:5], v[0:1], 0, s[86:87]
	s_mov_b32 m0, s12
	s_mov_b64 s[12:13], 0x60000
	v_add_u32_e32 v10, 0x3000, v134
	v_lshl_add_u64 v[4:5], v[0:1], 0, s[12:13]
	v_readfirstlane_b32 s12, v10
	s_mov_b32 m0, s12
	v_add_u32_e32 v10, 0x5000, v134
	v_add_u32_e32 v4, 0x4000, v134
	s_mov_b64 s[14:15], 0x20040
	v_readfirstlane_b32 s12, v4
	s_mov_b32 m0, s12
	v_readfirstlane_b32 s12, v10
	v_add_u32_e32 v10, 0x6000, v134
	v_lshl_add_u64 v[4:5], v[2:3], 0, s[96:97]
	s_mov_b32 m0, s12
	v_readfirstlane_b32 s12, v10
	v_add_u32_e32 v10, 0x7000, v134
	v_lshl_add_u64 v[4:5], v[0:1], 0, 64
	s_mov_b32 m0, s12
	v_readfirstlane_b32 s12, v10
	v_lshl_add_u64 v[4:5], v[0:1], 0, s[14:15]
	s_mov_b32 m0, s12
	s_mov_b64 s[12:13], 0x40040
	v_add_u32_e32 v10, 0x8000, v134
	v_lshl_add_u64 v[4:5], v[0:1], 0, s[12:13]
	v_readfirstlane_b32 s12, v10
	s_mov_b32 m0, s12
	s_mov_b64 s[12:13], 0x60040
	v_add_u32_e32 v4, 0x9000, v134
	v_lshl_add_u64 v[0:1], v[0:1], 0, s[12:13]
	v_readfirstlane_b32 s12, v4
	v_add_u32_e32 v4, 0xa000, v134
	s_mov_b32 m0, s12
	v_readfirstlane_b32 s12, v4
	v_lshl_add_u64 v[0:1], v[2:3], 0, 64
	s_mov_b32 m0, s12
	s_and_b32 s10, s4, 0xffffff80
	v_lshl_add_u64 v[0:1], v[2:3], 0, s[14:15]
	v_add_u32_e32 v2, 0xb000, v134
	s_and_b32 s11, s16, 0x3f00
	v_readfirstlane_b32 s12, v2
	s_mov_b32 m0, s12
	v_bitop3_b32 v2, v138, 3, v8 bitop3:0x48
	v_lshlrev_b32_e32 v0, 6, v138
	v_and_or_b32 v143, v0, s80, v6
	v_lshlrev_b32_e32 v0, 1, v138
	v_and_b32_e32 v1, 0x43, v138
	v_and_or_b32 v0, v0, 24, v1
	v_lshrrev_b32_e32 v1, 1, v138
	v_and_b32_e32 v1, 2, v1
	v_sub_u32_e32 v1, 0, v1
	v_bitop3_b32 v1, v1, v140, 2 bitop3:0x6c
	v_lshlrev_b32_e32 v1, 4, v1
	v_lshl_or_b32 v144, v0, 6, v1
	v_or_b32_e32 v0, 4, v0
	v_lshlrev_b32_e32 v1, 6, v0
	v_lshrrev_b32_e32 v0, 2, v0
	v_sub_u32_e32 v0, 0, v0
	v_bitop3_b32 v0, v0, v140, 3 bitop3:0x6c
	v_lshl_or_b32 v145, v0, 4, v1
	v_or_b32_e32 v0, s10, v7
	v_add_u32_e32 v0, v0, v9
	v_ashrrev_i32_e32 v1, 31, v0
	v_lshlrev_b64 v[0:1], 11, v[0:1]
	v_lshlrev_b32_e32 v2, 4, v2
	v_or_b32_e32 v0, v0, v2
	v_lshl_add_u64 v[128:129], s[74:75], 0, v[0:1]
	v_or_b32_e32 v0, s11, v7
	v_add_u32_e32 v0, v0, v9
	v_ashrrev_i32_e32 v1, 31, v0
	s_nop 0
	v_lshlrev_b64 v[0:1], 11, v[0:1]
	s_waitcnt lgkmcnt(0)
; #define WAIT_V(n) asm volatile("s_waitcnt vmcnt(%0)" ::"n"(n) : "memory")
; #define RAW_BARRIER() do { asm volatile("s_waitcnt lgkmcnt(0)" ::: "memory"); __builtin_amdgcn_s_barrier(); } while (0)
; #define DSR(dst, addr, off) asm volatile("ds_read_b128 %0, %1 offset:%2" : "=v"(dst) : "v"(addr), "n"(off) : "memory")
; __device__ __forceinline__ void gb_step(const u16* ga, const u16* gw, size_t a64, size_t w64, int ko, bool issue, ...
;     ...
;   const unsigned rdb = (unsigned)(size_t)(__attribute__((address_space(3))) const char*)rd;
;   const unsigned ab = rdb + (unsigned)(((wm * 128 + (lane & 15)) * GST + rsw) * 2);
;   const int wr0 = wn * 64 + (((lane & 15) >> 2) << 3) + (lane & 3);
;   const unsigned bb0 = rdb + (unsigned)((256 * GST + wr0 * GST + GSW(wr0, lane >> 4)) * 2);
;   const unsigned bb1 = rdb + (unsigned)((256 * GST + (wr0 + 4) * GST + GSW(wr0 + 4, lane >> 4)) * 2);
;   bf16x8 wf0, wf1, wf2, wf3, xf0, xf1, xf2, xf3, xf4, xf5, xf6, xf7;
;     ...
;   DSR(wf0, bb0, 0); DSR(wf1, bb1, 0); DSR(wf2, bb0, 2048); DSR(wf3, bb1, 2048);
;   DSR(xf0, ab, 0); DSR(xf1, ab, 1024); DSR(xf2, ab, 2048); DSR(xf3, ab, 3072);
;   DSR(xf4, ab, 4096); DSR(xf5, ab, 5120); DSR(xf6, ab, 6144); DSR(xf7, ab, 7168);
; template <class F>
; __device__ __forceinline__ void gemm_big(const ALbf& al, const u16* __restrict__ Wt, int K, int m0, int n0, const F& f, u16* sm) {
;     ...
;   f32x4 acc[4][8];
; #pragma unroll
;   for (int i = 0; i < 4; i++)
; #pragma unroll
;     for (int j = 0; j < 8; j++) acc[i][j] = (f32x4){0.f, 0.f, 0.f, 0.f};
;   const int srow = lane >> 2;
;   const int scol = ((lane & 3) ^ ((0 - (srow >> 2)) & 3)) * 8;
;   const u16* ga = al.A + (size_t)(m0 + wave * 16 + srow) * al.lda + scol;
;   const u16* gw = Wt + (size_t)(n0 + wave * 16 + srow) * K + scol;
;   const size_t a64 = (size_t)64 * al.lda, w64 = (size_t)64 * K;
;   const int nk = K >> 5;
;   WAIT_V(0);
;   gb_issue(ga, gw, a64, w64, 0, sm, wave);
;   gb_issue(ga, gw, a64, w64, 32, sm + GB_STAGE_EL, wave);
;   WAIT_V(6);
;   RAW_BARRIER();
	v_or_b32_e32 v0, v0, v2
	v_lshl_add_u64 v[130:131], s[30:31], 0, v[0:1]
	v_mov_b32_e32 v0, 0
	s_mov_b32 s94, 0
	s_mov_b64 s[10:11], 0
	s_mov_b32 s95, 0
	v_mov_b32_e32 v1, v0
	v_mov_b32_e32 v2, v0
	v_mov_b32_e32 v3, v0
	v_mov_b32_e32 v4, v0
	v_mov_b32_e32 v5, v0
	v_mov_b32_e32 v6, v0
	v_mov_b32_e32 v7, v0
	v_mov_b32_e32 v48, v0
	v_mov_b32_e32 v49, v0
	v_mov_b32_e32 v50, v0
	v_mov_b32_e32 v51, v0
	v_mov_b32_e32 v52, v0
	v_mov_b32_e32 v53, v0
	v_mov_b32_e32 v54, v0
	v_mov_b32_e32 v55, v0
	v_mov_b32_e32 v8, v0
	v_mov_b32_e32 v9, v0
	v_mov_b32_e32 v10, v0
	v_mov_b32_e32 v11, v0
	v_mov_b32_e32 v12, v0
	v_mov_b32_e32 v13, v0
	v_mov_b32_e32 v14, v0
	v_mov_b32_e32 v15, v0
	v_mov_b32_e32 v64, v0
	v_mov_b32_e32 v65, v0
	v_mov_b32_e32 v66, v0
	v_mov_b32_e32 v67, v0
	v_mov_b32_e32 v72, v0
	v_mov_b32_e32 v73, v0
	v_mov_b32_e32 v74, v0
	v_mov_b32_e32 v75, v0
	v_mov_b32_e32 v16, v0
	v_mov_b32_e32 v17, v0
	v_mov_b32_e32 v18, v0
	v_mov_b32_e32 v19, v0
	v_mov_b32_e32 v20, v0
	v_mov_b32_e32 v21, v0
	v_mov_b32_e32 v22, v0
	v_mov_b32_e32 v23, v0
	v_mov_b32_e32 v80, v0
	v_mov_b32_e32 v81, v0
	v_mov_b32_e32 v82, v0
	v_mov_b32_e32 v83, v0
	v_mov_b32_e32 v84, v0
	v_mov_b32_e32 v85, v0
	v_mov_b32_e32 v86, v0
	v_mov_b32_e32 v87, v0
	v_mov_b32_e32 v24, v0
	v_mov_b32_e32 v25, v0
	v_mov_b32_e32 v26, v0
	v_mov_b32_e32 v27, v0
	v_mov_b32_e32 v28, v0
	v_mov_b32_e32 v29, v0
	v_mov_b32_e32 v30, v0
	v_mov_b32_e32 v31, v0
	v_mov_b32_e32 v88, v0
	v_mov_b32_e32 v89, v0
	v_mov_b32_e32 v90, v0
	v_mov_b32_e32 v91, v0
	v_mov_b32_e32 v92, v0
	v_mov_b32_e32 v93, v0
	v_mov_b32_e32 v94, v0
	v_mov_b32_e32 v95, v0
	v_mov_b32_e32 v32, v0
	v_mov_b32_e32 v33, v0
	v_mov_b32_e32 v34, v0
	v_mov_b32_e32 v35, v0
	v_mov_b32_e32 v36, v0
	v_mov_b32_e32 v37, v0
	v_mov_b32_e32 v38, v0
	v_mov_b32_e32 v39, v0
	v_mov_b32_e32 v96, v0
	v_mov_b32_e32 v97, v0
	v_mov_b32_e32 v98, v0
	v_mov_b32_e32 v99, v0
	v_mov_b32_e32 v100, v0
	v_mov_b32_e32 v101, v0
	v_mov_b32_e32 v102, v0
	v_mov_b32_e32 v103, v0
	v_mov_b32_e32 v40, v0
	v_mov_b32_e32 v41, v0
	v_mov_b32_e32 v42, v0
	v_mov_b32_e32 v43, v0
	v_mov_b32_e32 v44, v0
	v_mov_b32_e32 v45, v0
	v_mov_b32_e32 v46, v0
	v_mov_b32_e32 v47, v0
	v_mov_b32_e32 v104, v0
	v_mov_b32_e32 v105, v0
	v_mov_b32_e32 v106, v0
	v_mov_b32_e32 v107, v0
	v_mov_b32_e32 v108, v0
	v_mov_b32_e32 v109, v0
	v_mov_b32_e32 v110, v0
	v_mov_b32_e32 v111, v0
	v_mov_b32_e32 v56, v0
	v_mov_b32_e32 v57, v0
	v_mov_b32_e32 v58, v0
	v_mov_b32_e32 v59, v0
	v_mov_b32_e32 v60, v0
	v_mov_b32_e32 v61, v0
	v_mov_b32_e32 v62, v0
	v_mov_b32_e32 v63, v0
	v_mov_b32_e32 v112, v0
	v_mov_b32_e32 v113, v0
	v_mov_b32_e32 v114, v0
	v_mov_b32_e32 v115, v0
	v_mov_b32_e32 v116, v0
	v_mov_b32_e32 v117, v0
	v_mov_b32_e32 v118, v0
	v_mov_b32_e32 v119, v0
	v_mov_b32_e32 v68, v0
	v_mov_b32_e32 v69, v0
	v_mov_b32_e32 v70, v0
	v_mov_b32_e32 v71, v0
	v_mov_b32_e32 v76, v0
	v_mov_b32_e32 v77, v0
	v_mov_b32_e32 v78, v0
	v_mov_b32_e32 v79, v0
	v_mov_b32_e32 v120, v0
	v_mov_b32_e32 v121, v0
	v_mov_b32_e32 v122, v0
	v_mov_b32_e32 v123, v0
	v_mov_b32_e32 v124, v0
	v_mov_b32_e32 v125, v0
	v_mov_b32_e32 v126, v0
	v_mov_b32_e32 v127, v0
	v_readfirstlane_b32 s10, v130
	v_readfirstlane_b32 s11, v131
	v_readfirstlane_b32 s12, v128
	v_readfirstlane_b32 s13, v129
	v_readfirstlane_b32 s95, v134
	v_and_b32_e32 v176, 63, v132
	v_lshrrev_b32_e32 v177, 6, v132
	v_lshrrev_b32_e32 v178, 3, v176
	v_and_b32_e32 v179, 7, v176
	v_lshrrev_b32_e32 v180, 4, v176
	v_and_b32_e32 v181, 1, v177
	v_lshrrev_b32_e32 v182, 1, v177
	v_lshl_add_u32 v183, v181, 2, v180
	v_xor_b32_e32 v183, v179, v183
	v_lshl_add_u32 v184, v177, 3, v178
	v_lshlrev_b32_e32 v188, 11, v184
	v_lshl_add_u32 v128, v183, 4, v188
	v_add_u32_e32 v129, 0x10000, v128
	v_add_u32_e32 v130, 0x40000, v128
	v_add_u32_e32 v131, 0x50000, v128
	v_bfe_u32 v185, v178, 1, 1
	v_lshl_or_b32 v185, v181, 1, v185
	v_lshl_or_b32 v185, v182, 2, v185
	v_xor_b32_e32 v185, v179, v185
	v_lshl_add_u32 v134, v185, 4, v188
	v_add_u32_e32 v143, 0x10000, v134
	v_add_u32_e32 v196, 0x20000, v134
	v_add_u32_e32 v197, 0x30000, v134
	v_and_b32_e32 v186, 15, v176
	v_bfe_u32 v187, v176, 1, 3
	v_xor_b32_e32 v187, v180, v187
	v_lshlrev_b32_e32 v187, 4, v187
	v_lshl_add_u32 v188, v182, 6, v186
	v_lshl_add_u32 v219, v188, 7, v187
	v_xor_b32_e32 v228, 64, v219
	v_lshrrev_b32_e32 v189, 2, v186
	v_lshlrev_b32_e32 v189, 3, v189
	v_and_b32_e32 v188, 3, v186
	v_add_u32_e32 v189, v189, v188
	v_lshl_add_u32 v189, v181, 6, v189
	v_lshl_add_u32 v231, v189, 7, v187
	v_xor_b32_e32 v216, 64, v231
	s_lshl_b32 s15, s95, 5
	s_sub_u32 s10, s10, s15
	s_subb_u32 s11, s11, 0
	s_sub_u32 s12, s12, s15
	s_subb_u32 s13, s13, 0
	s_add_u32 m0, s95, 0x8000
	s_nop 0
	global_load_lds_dwordx4 v128, s[10:11]
	s_add_u32 m0, s95, 0x9000
	s_nop 0
	global_load_lds_dwordx4 v129, s[10:11]
	s_add_u32 m0, s95, 0xa000
	s_nop 0
	global_load_lds_dwordx4 v130, s[10:11]
	s_add_u32 m0, s95, 0xb000
	s_nop 0
	global_load_lds_dwordx4 v131, s[10:11]
	s_add_u32 s10, s10, 0x20000
	s_addc_u32 s11, s11, 0
	s_add_u32 m0, s95, 0xc000
	s_nop 0
	global_load_lds_dwordx4 v128, s[10:11]
	s_add_u32 m0, s95, 0xd000
	s_nop 0
	global_load_lds_dwordx4 v129, s[10:11]
	s_add_u32 m0, s95, 0xe000
	s_nop 0
	global_load_lds_dwordx4 v130, s[10:11]
	s_add_u32 m0, s95, 0xf000
	s_nop 0
	global_load_lds_dwordx4 v131, s[10:11]
	s_add_u32 s10, s10, 0xfffe0080
	s_addc_u32 s11, s11, -1
	s_add_u32 m0, s95, 0x0
	s_nop 0
	global_load_lds_dwordx4 v134, s[12:13]
	s_add_u32 m0, s95, 0x1000
	s_nop 0
	global_load_lds_dwordx4 v143, s[12:13]
	s_add_u32 m0, s95, 0x2000
	s_nop 0
	global_load_lds_dwordx4 v196, s[12:13]
	s_add_u32 m0, s95, 0x3000
	s_nop 0
	global_load_lds_dwordx4 v197, s[12:13]
	s_add_u32 s12, s12, 0x80
	s_addc_u32 s13, s13, 0
	s_add_u32 m0, s95, 0x4000
	s_nop 0
	global_load_lds_dwordx4 v134, s[12:13]
	s_add_u32 m0, s95, 0x5000
	s_nop 0
	global_load_lds_dwordx4 v143, s[12:13]
	s_add_u32 m0, s95, 0x6000
	s_nop 0
	global_load_lds_dwordx4 v196, s[12:13]
	s_add_u32 m0, s95, 0x7000
	s_nop 0
	global_load_lds_dwordx4 v197, s[12:13]
	s_add_u32 s12, s12, 0x80
	s_addc_u32 s13, s13, 0
	s_waitcnt vmcnt(0)
	s_barrier
	s_mov_b32 s14, 0
	s_mov_b32 s94, 0
	ds_read_b128 v[144:147], v219 offset:32768
	ds_read_b128 v[148:151], v219 offset:34816
	ds_read_b128 v[152:155], v219 offset:36864
	ds_read_b128 v[156:159], v219 offset:38912
	ds_read_b128 v[160:163], v228 offset:32768
	ds_read_b128 v[164:167], v228 offset:34816
	ds_read_b128 v[168:171], v228 offset:36864
	ds_read_b128 v[172:175], v228 offset:38912
	v_add_u32_e32 v248, s14, v231
	ds_read_b128 v[236:239], v248 offset:0
	ds_read_b128 v[240:243], v248 offset:512
	ds_read_b128 v[244:247], v248 offset:4096
	ds_read_b128 v[248:251], v248 offset:4608
	s_waitcnt lgkmcnt(0)
	s_barrier

; __device__ __forceinline__ int ltid() { int t = threadIdx.x; asm volatile("" : "+v"(t)); return t; }
; #define WAIT_V(n) asm volatile("s_waitcnt vmcnt(%0)" ::"n"(n) : "memory")
; template <class F>
; __device__ __forceinline__ void gemm_big(const ALbf& al, const u16* __restrict__ Wt, int K, int m0, int n0, const F& f, u16* sm) {
;   const int tid = ltid(), lane = tid & 63, wave = tid >> 6;
;   const int wm = wave >> 1, wn = wave & 1;
;   const int rsw = GSW(lane & 15, lane >> 4);
;   f32x4 acc[4][8];
; #pragma unroll
;   for (int i = 0; i < 4; i++)
; #pragma unroll
;     for (int j = 0; j < 8; j++) acc[i][j] = (f32x4){0.f, 0.f, 0.f, 0.f};
;   const int srow = lane >> 2;
;   const int scol = ((lane & 3) ^ ((0 - (srow >> 2)) & 3)) * 8;
;   const u16* ga = al.A + (size_t)(m0 + wave * 16 + srow) * al.lda + scol;
;   const u16* gw = Wt + (size_t)(n0 + wave * 16 + srow) * K + scol;
;   const size_t a64 = (size_t)64 * al.lda, w64 = (size_t)64 * K;
;   const int nk = K >> 5;
;   WAIT_V(0);
;   gb_issue(ga, gw, a64, w64, 0, sm, wave);
.LBB0_242:
	v_mov_b32_e32 v138, v132
	s_lshl_b32 s10, s17, 8
	v_lshrrev_b32_e32 v0, 2, v138
	v_bfe_u32 v140, v138, 4, 2
	v_sub_u32_e32 v0, 0, v0
	v_bitop3_b32 v0, v140, v0, 3 bitop3:0x78
	v_lshlrev_b32_e32 v6, 4, v0
	v_lshrrev_b32_e32 v0, 4, v138
	v_ashrrev_i32_e32 v4, 6, v138
	v_sub_u32_e32 v8, 0, v0
	s_and_b32 s61, s10, 0x3f00
	s_lshl_b32 s10, s17, 1
	v_bfe_u32 v7, v138, 2, 4
	v_xor_b32_e32 v2, v138, v8
	v_lshlrev_b32_e32 v9, 4, v4
	s_load_dwordx16 s[64:79], s[0:1], 0x160
	s_and_b32 s60, s10, 0xffffff80
	v_or_b32_e32 v3, v7, v9
	v_lshlrev_b32_e32 v2, 4, v2
	v_add_u32_e32 v0, s61, v3
	v_and_b32_e32 v134, 48, v2
	v_add_u32_e32 v2, s60, v3
	v_ashrrev_i32_e32 v1, 31, v0
	v_ashrrev_i32_e32 v3, 31, v2
	v_lshlrev_b64 v[0:1], 13, v[0:1]
	v_lshlrev_b64 v[2:3], 13, v[2:3]
	v_lshl_add_u64 v[0:1], s[22:23], 0, v[0:1]
	s_waitcnt lgkmcnt(0)
	v_lshl_add_u64 v[2:3], s[76:77], 0, v[2:3]
	v_lshl_add_u64 v[0:1], v[0:1], 0, v[134:135]
	v_lshl_add_u64 v[2:3], v[2:3], 0, v[134:135]
	v_lshlrev_b32_e32 v134, 10, v4
	v_add_u32_e32 v10, 0x1000, v134
	v_readfirstlane_b32 s10, v134
	s_nop 0
	s_mov_b32 m0, s10
	v_readfirstlane_b32 s10, v10
	v_lshl_add_u64 v[4:5], v[0:1], 0, s[92:93]
	s_mov_b32 m0, s10
	s_mov_b64 s[10:11], 0x100000
	v_add_u32_e32 v10, 0x2000, v134
	v_lshl_add_u64 v[4:5], v[0:1], 0, s[10:11]
	v_readfirstlane_b32 s10, v10
	s_mov_b32 m0, s10
	s_mov_b64 s[10:11], 0x180000
	v_add_u32_e32 v10, 0x3000, v134
	v_lshl_add_u64 v[4:5], v[0:1], 0, s[10:11]
	v_readfirstlane_b32 s10, v10
	s_mov_b32 m0, s10
	v_add_u32_e32 v10, 0x5000, v134
	v_add_u32_e32 v4, 0x4000, v134
	s_mov_b64 s[14:15], 0x80040
	v_readfirstlane_b32 s10, v4
	s_mov_b32 m0, s10
	v_readfirstlane_b32 s10, v10
	v_add_u32_e32 v10, 0x6000, v134
	v_lshl_add_u64 v[4:5], v[2:3], 0, s[92:93]
	s_mov_b32 m0, s10
	v_readfirstlane_b32 s10, v10
	v_add_u32_e32 v10, 0x7000, v134
	v_lshl_add_u64 v[4:5], v[0:1], 0, 64
	s_mov_b32 m0, s10
	v_readfirstlane_b32 s10, v10
	v_lshl_add_u64 v[4:5], v[0:1], 0, s[14:15]
	s_mov_b32 m0, s10
	s_mov_b64 s[10:11], 0x100040
	v_add_u32_e32 v10, 0x8000, v134
	v_lshl_add_u64 v[4:5], v[0:1], 0, s[10:11]
	v_readfirstlane_b32 s10, v10
	s_mov_b32 m0, s10
	s_mov_b64 s[10:11], 0x180040
	v_add_u32_e32 v4, 0x9000, v134
	v_lshl_add_u64 v[0:1], v[0:1], 0, s[10:11]
	v_readfirstlane_b32 s10, v4
	v_add_u32_e32 v4, 0xa000, v134
	s_mov_b32 m0, s10
	v_readfirstlane_b32 s10, v4
	v_lshl_add_u64 v[0:1], v[2:3], 0, 64
	s_mov_b32 m0, s10
	s_and_b32 s12, s4, 0xffffff80
	v_lshl_add_u64 v[0:1], v[2:3], 0, s[14:15]
	v_add_u32_e32 v2, 0xb000, v134
	s_and_b32 s13, s16, 0x3f00
	v_readfirstlane_b32 s10, v2
	s_mov_b32 m0, s10
	v_bitop3_b32 v2, v138, 3, v8 bitop3:0x48
	v_lshlrev_b32_e32 v0, 6, v138
	v_and_or_b32 v143, v0, s80, v6
	v_lshlrev_b32_e32 v0, 1, v138
	v_and_b32_e32 v1, 0x43, v138
	v_and_or_b32 v0, v0, 24, v1
	v_lshrrev_b32_e32 v1, 1, v138
	v_and_b32_e32 v1, 2, v1
	v_sub_u32_e32 v1, 0, v1
	v_bitop3_b32 v1, v1, v140, 2 bitop3:0x6c
	v_lshlrev_b32_e32 v1, 4, v1
	v_lshl_or_b32 v144, v0, 6, v1
	v_or_b32_e32 v0, 4, v0
	v_lshlrev_b32_e32 v1, 6, v0
	v_lshrrev_b32_e32 v0, 2, v0
	v_sub_u32_e32 v0, 0, v0
	v_bitop3_b32 v0, v0, v140, 3 bitop3:0x6c
	v_lshl_or_b32 v145, v0, 4, v1
	v_or_b32_e32 v0, s12, v7
	v_add_u32_e32 v0, v0, v9
	v_ashrrev_i32_e32 v1, 31, v0
	v_lshlrev_b64 v[0:1], 13, v[0:1]
	v_lshlrev_b32_e32 v2, 4, v2
	v_or_b32_e32 v0, v0, v2
	v_lshl_add_u64 v[128:129], s[76:77], 0, v[0:1]
	v_or_b32_e32 v0, s13, v7
	v_add_u32_e32 v0, v0, v9
	v_ashrrev_i32_e32 v1, 31, v0
	s_nop 0
	v_lshlrev_b64 v[0:1], 13, v[0:1]
	s_waitcnt lgkmcnt(0)
; #define WAIT_V(n) asm volatile("s_waitcnt vmcnt(%0)" ::"n"(n) : "memory")
; #define RAW_BARRIER() do { asm volatile("s_waitcnt lgkmcnt(0)" ::: "memory"); __builtin_amdgcn_s_barrier(); } while (0)
; #define DSR(dst, addr, off) asm volatile("ds_read_b128 %0, %1 offset:%2" : "=v"(dst) : "v"(addr), "n"(off) : "memory")
; __device__ __forceinline__ void gb_step(const u16* ga, const u16* gw, size_t a64, size_t w64, int ko, bool issue, ...
;     ...
;   const unsigned rdb = (unsigned)(size_t)(__attribute__((address_space(3))) const char*)rd;
;   const unsigned ab = rdb + (unsigned)(((wm * 128 + (lane & 15)) * GST + rsw) * 2);
;   const int wr0 = wn * 64 + (((lane & 15) >> 2) << 3) + (lane & 3);
;   const unsigned bb0 = rdb + (unsigned)((256 * GST + wr0 * GST + GSW(wr0, lane >> 4)) * 2);
;   const unsigned bb1 = rdb + (unsigned)((256 * GST + (wr0 + 4) * GST + GSW(wr0 + 4, lane >> 4)) * 2);
;   bf16x8 wf0, wf1, wf2, wf3, xf0, xf1, xf2, xf3, xf4, xf5, xf6, xf7;
;     ...
;   DSR(wf0, bb0, 0); DSR(wf1, bb1, 0); DSR(wf2, bb0, 2048); DSR(wf3, bb1, 2048);
;   DSR(xf0, ab, 0); DSR(xf1, ab, 1024); DSR(xf2, ab, 2048); DSR(xf3, ab, 3072);
;   DSR(xf4, ab, 4096); DSR(xf5, ab, 5120); DSR(xf6, ab, 6144); DSR(xf7, ab, 7168);
; template <class F>
; __device__ __forceinline__ void gemm_big(const ALbf& al, const u16* __restrict__ Wt, int K, int m0, int n0, const F& f, u16* sm) {
;     ...
;   f32x4 acc[4][8];
; #pragma unroll
;   for (int i = 0; i < 4; i++)
; #pragma unroll
;     for (int j = 0; j < 8; j++) acc[i][j] = (f32x4){0.f, 0.f, 0.f, 0.f};
;   const int srow = lane >> 2;
;   const int scol = ((lane & 3) ^ ((0 - (srow >> 2)) & 3)) * 8;
;   const u16* ga = al.A + (size_t)(m0 + wave * 16 + srow) * al.lda + scol;
;   const u16* gw = Wt + (size_t)(n0 + wave * 16 + srow) * K + scol;
;   const size_t a64 = (size_t)64 * al.lda, w64 = (size_t)64 * K;
;   const int nk = K >> 5;
;   WAIT_V(0);
;   gb_issue(ga, gw, a64, w64, 0, sm, wave);
;   gb_issue(ga, gw, a64, w64, 32, sm + GB_STAGE_EL, wave);
;   WAIT_V(6);
;   RAW_BARRIER();
	v_or_b32_e32 v0, v0, v2
	v_lshl_add_u64 v[130:131], s[22:23], 0, v[0:1]
	v_mov_b32_e32 v0, 0
	s_mov_b32 s94, 0
	s_mov_b64 s[10:11], 0
	s_mov_b32 s95, 0
	v_mov_b32_e32 v1, v0
	v_mov_b32_e32 v2, v0
	v_mov_b32_e32 v3, v0
	v_mov_b32_e32 v4, v0
	v_mov_b32_e32 v5, v0
	v_mov_b32_e32 v6, v0
	v_mov_b32_e32 v7, v0
	v_mov_b32_e32 v32, v0
	v_mov_b32_e32 v33, v0
	v_mov_b32_e32 v34, v0
	v_mov_b32_e32 v35, v0
	v_mov_b32_e32 v36, v0
	v_mov_b32_e32 v37, v0
	v_mov_b32_e32 v38, v0
	v_mov_b32_e32 v39, v0
	v_mov_b32_e32 v8, v0
	v_mov_b32_e32 v9, v0
	v_mov_b32_e32 v10, v0
	v_mov_b32_e32 v11, v0
	v_mov_b32_e32 v12, v0
	v_mov_b32_e32 v13, v0
	v_mov_b32_e32 v14, v0
	v_mov_b32_e32 v15, v0
	v_mov_b32_e32 v48, v0
	v_mov_b32_e32 v49, v0
	v_mov_b32_e32 v50, v0
	v_mov_b32_e32 v51, v0
	v_mov_b32_e32 v52, v0
	v_mov_b32_e32 v53, v0
	v_mov_b32_e32 v54, v0
	v_mov_b32_e32 v55, v0
	v_mov_b32_e32 v16, v0
	v_mov_b32_e32 v17, v0
	v_mov_b32_e32 v18, v0
	v_mov_b32_e32 v19, v0
	v_mov_b32_e32 v20, v0
	v_mov_b32_e32 v21, v0
	v_mov_b32_e32 v22, v0
	v_mov_b32_e32 v23, v0
	v_mov_b32_e32 v64, v0
	v_mov_b32_e32 v65, v0
	v_mov_b32_e32 v66, v0
	v_mov_b32_e32 v67, v0
	v_mov_b32_e32 v72, v0
	v_mov_b32_e32 v73, v0
	v_mov_b32_e32 v74, v0
	v_mov_b32_e32 v75, v0
	v_mov_b32_e32 v24, v0
	v_mov_b32_e32 v25, v0
	v_mov_b32_e32 v26, v0
	v_mov_b32_e32 v27, v0
	v_mov_b32_e32 v28, v0
	v_mov_b32_e32 v29, v0
	v_mov_b32_e32 v30, v0
	v_mov_b32_e32 v31, v0
	v_mov_b32_e32 v88, v0
	v_mov_b32_e32 v89, v0
	v_mov_b32_e32 v90, v0
	v_mov_b32_e32 v91, v0
	v_mov_b32_e32 v92, v0
	v_mov_b32_e32 v93, v0
	v_mov_b32_e32 v94, v0
	v_mov_b32_e32 v95, v0
	v_mov_b32_e32 v40, v0
	v_mov_b32_e32 v41, v0
	v_mov_b32_e32 v42, v0
	v_mov_b32_e32 v43, v0
	v_mov_b32_e32 v44, v0
	v_mov_b32_e32 v45, v0
	v_mov_b32_e32 v46, v0
	v_mov_b32_e32 v47, v0
	v_mov_b32_e32 v96, v0
	v_mov_b32_e32 v97, v0
	v_mov_b32_e32 v98, v0
	v_mov_b32_e32 v99, v0
	v_mov_b32_e32 v100, v0
	v_mov_b32_e32 v101, v0
	v_mov_b32_e32 v102, v0
	v_mov_b32_e32 v103, v0
	v_mov_b32_e32 v56, v0
	v_mov_b32_e32 v57, v0
	v_mov_b32_e32 v58, v0
	v_mov_b32_e32 v59, v0
	v_mov_b32_e32 v60, v0
	v_mov_b32_e32 v61, v0
	v_mov_b32_e32 v62, v0
	v_mov_b32_e32 v63, v0
	v_mov_b32_e32 v104, v0
	v_mov_b32_e32 v105, v0
	v_mov_b32_e32 v106, v0
	v_mov_b32_e32 v107, v0
	v_mov_b32_e32 v108, v0
	v_mov_b32_e32 v109, v0
	v_mov_b32_e32 v110, v0
	v_mov_b32_e32 v111, v0
	v_mov_b32_e32 v68, v0
	v_mov_b32_e32 v69, v0
	v_mov_b32_e32 v70, v0
	v_mov_b32_e32 v71, v0
	v_mov_b32_e32 v76, v0
	v_mov_b32_e32 v77, v0
	v_mov_b32_e32 v78, v0
	v_mov_b32_e32 v79, v0
	v_mov_b32_e32 v112, v0
	v_mov_b32_e32 v113, v0
	v_mov_b32_e32 v114, v0
	v_mov_b32_e32 v115, v0
	v_mov_b32_e32 v116, v0
	v_mov_b32_e32 v117, v0
	v_mov_b32_e32 v118, v0
	v_mov_b32_e32 v119, v0
	v_mov_b32_e32 v80, v0
	v_mov_b32_e32 v81, v0
	v_mov_b32_e32 v82, v0
	v_mov_b32_e32 v83, v0
	v_mov_b32_e32 v84, v0
	v_mov_b32_e32 v85, v0
	v_mov_b32_e32 v86, v0
	v_mov_b32_e32 v87, v0
	v_mov_b32_e32 v120, v0
	v_mov_b32_e32 v121, v0
	v_mov_b32_e32 v122, v0
	v_mov_b32_e32 v123, v0
	v_mov_b32_e32 v124, v0
	v_mov_b32_e32 v125, v0
	v_mov_b32_e32 v126, v0
	v_mov_b32_e32 v127, v0
	v_readfirstlane_b32 s10, v130
	v_readfirstlane_b32 s11, v131
	v_readfirstlane_b32 s12, v128
	v_readfirstlane_b32 s13, v129
	v_readfirstlane_b32 s95, v134
	v_and_b32_e32 v176, 63, v132
	v_lshrrev_b32_e32 v177, 6, v132
	v_lshrrev_b32_e32 v178, 3, v176
	v_and_b32_e32 v179, 7, v176
	v_lshrrev_b32_e32 v180, 4, v176
	v_and_b32_e32 v181, 1, v177
	v_lshrrev_b32_e32 v182, 1, v177
	v_lshl_add_u32 v183, v181, 2, v180
	v_xor_b32_e32 v183, v179, v183
	v_lshl_add_u32 v184, v177, 3, v178
	v_lshlrev_b32_e32 v188, 13, v184
	v_lshl_add_u32 v128, v183, 4, v188
	v_add_u32_e32 v129, 0x40000, v128
	v_add_u32_e32 v130, 0x100000, v128
	v_add_u32_e32 v131, 0x140000, v128
	v_bfe_u32 v185, v178, 1, 1
	v_lshl_or_b32 v185, v181, 1, v185
	v_lshl_or_b32 v185, v182, 2, v185
	v_xor_b32_e32 v185, v179, v185
	v_lshl_add_u32 v134, v185, 4, v188
	v_add_u32_e32 v143, 0x40000, v134
	v_add_u32_e32 v196, 0x80000, v134
	v_add_u32_e32 v197, 0xc0000, v134
	v_and_b32_e32 v186, 15, v176
	v_bfe_u32 v187, v176, 1, 3
	v_xor_b32_e32 v187, v180, v187
	v_lshlrev_b32_e32 v187, 4, v187
	v_lshl_add_u32 v188, v182, 6, v186
	v_lshl_add_u32 v219, v188, 7, v187
	v_xor_b32_e32 v228, 64, v219
	v_lshrrev_b32_e32 v189, 2, v186
	v_lshlrev_b32_e32 v189, 3, v189
	v_and_b32_e32 v188, 3, v186
	v_add_u32_e32 v189, v189, v188
	v_lshl_add_u32 v189, v181, 6, v189
	v_lshl_add_u32 v231, v189, 7, v187
	v_xor_b32_e32 v216, 64, v231
	s_lshl_b32 s15, s95, 7
	s_sub_u32 s10, s10, s15
	s_subb_u32 s11, s11, 0
	s_sub_u32 s12, s12, s15
	s_subb_u32 s13, s13, 0
	s_add_u32 m0, s95, 0x8000
	s_nop 0
	global_load_lds_dwordx4 v128, s[10:11]
	s_add_u32 m0, s95, 0x9000
	s_nop 0
	global_load_lds_dwordx4 v129, s[10:11]
	s_add_u32 m0, s95, 0xa000
	s_nop 0
	global_load_lds_dwordx4 v130, s[10:11]
	s_add_u32 m0, s95, 0xb000
	s_nop 0
	global_load_lds_dwordx4 v131, s[10:11]
	s_add_u32 s10, s10, 0x80000
	s_addc_u32 s11, s11, 0
	s_add_u32 m0, s95, 0xc000
	s_nop 0
	global_load_lds_dwordx4 v128, s[10:11]
	s_add_u32 m0, s95, 0xd000
	s_nop 0
	global_load_lds_dwordx4 v129, s[10:11]
	s_add_u32 m0, s95, 0xe000
	s_nop 0
	global_load_lds_dwordx4 v130, s[10:11]
	s_add_u32 m0, s95, 0xf000
	s_nop 0
	global_load_lds_dwordx4 v131, s[10:11]
	s_add_u32 s10, s10, 0xfff80080
	s_addc_u32 s11, s11, -1
	s_add_u32 m0, s95, 0x0
	s_nop 0
	global_load_lds_dwordx4 v134, s[12:13]
	s_add_u32 m0, s95, 0x1000
	s_nop 0
	global_load_lds_dwordx4 v143, s[12:13]
	s_add_u32 m0, s95, 0x2000
	s_nop 0
	global_load_lds_dwordx4 v196, s[12:13]
	s_add_u32 m0, s95, 0x3000
	s_nop 0
	global_load_lds_dwordx4 v197, s[12:13]
	s_add_u32 s12, s12, 0x80
	s_addc_u32 s13, s13, 0
	s_add_u32 m0, s95, 0x4000
	s_nop 0
	global_load_lds_dwordx4 v134, s[12:13]
	s_add_u32 m0, s95, 0x5000
	s_nop 0
	global_load_lds_dwordx4 v143, s[12:13]
	s_add_u32 m0, s95, 0x6000
	s_nop 0
	global_load_lds_dwordx4 v196, s[12:13]
	s_add_u32 m0, s95, 0x7000
	s_nop 0
	global_load_lds_dwordx4 v197, s[12:13]
	s_add_u32 s12, s12, 0x80
	s_addc_u32 s13, s13, 0
	s_waitcnt vmcnt(0)
	s_barrier
	s_mov_b32 s14, 0
	s_mov_b32 s94, 0
	ds_read_b128 v[144:147], v219 offset:32768
	ds_read_b128 v[148:151], v219 offset:34816
	ds_read_b128 v[152:155], v219 offset:36864
	ds_read_b128 v[156:159], v219 offset:38912
	ds_read_b128 v[160:163], v228 offset:32768
	ds_read_b128 v[164:167], v228 offset:34816
	ds_read_b128 v[168:171], v228 offset:36864
	ds_read_b128 v[172:175], v228 offset:38912
	v_add_u32_e32 v248, s14, v231
	ds_read_b128 v[236:239], v248 offset:0
	ds_read_b128 v[240:243], v248 offset:512
	ds_read_b128 v[244:247], v248 offset:4096
	ds_read_b128 v[248:251], v248 offset:4608
	s_waitcnt lgkmcnt(0)
	s_barrier

; __device__ __forceinline__ int ltid() { int t = threadIdx.x; asm volatile("" : "+v"(t)); return t; }
; #define WAIT_V(n) asm volatile("s_waitcnt vmcnt(%0)" ::"n"(n) : "memory")
; template <class F>
; __device__ __forceinline__ void gemm_big(const ALbf& al, const u16* __restrict__ Wt, int K, int m0, int n0, const F& f, u16* sm) {
;   const int tid = ltid(), lane = tid & 63, wave = tid >> 6;
;   const int wm = wave >> 1, wn = wave & 1;
;   const int rsw = GSW(lane & 15, lane >> 4);
;   f32x4 acc[4][8];
; #pragma unroll
;   for (int i = 0; i < 4; i++)
; #pragma unroll
;     for (int j = 0; j < 8; j++) acc[i][j] = (f32x4){0.f, 0.f, 0.f, 0.f};
;   const int srow = lane >> 2;
;   const int scol = ((lane & 3) ^ ((0 - (srow >> 2)) & 3)) * 8;
;   const u16* ga = al.A + (size_t)(m0 + wave * 16 + srow) * al.lda + scol;
;   const u16* gw = Wt + (size_t)(n0 + wave * 16 + srow) * K + scol;
;   const size_t a64 = (size_t)64 * al.lda, w64 = (size_t)64 * K;
;   const int nk = K >> 5;
;   WAIT_V(0);
;   gb_issue(ga, gw, a64, w64, 0, sm, wave);
.LBB0_257:
	v_mov_b32_e32 v138, v132
	s_lshl_b32 s10, s15, 8
	v_lshrrev_b32_e32 v0, 2, v138
	v_bfe_u32 v140, v138, 4, 2
	v_sub_u32_e32 v0, 0, v0
	v_bitop3_b32 v0, v140, v0, 3 bitop3:0x78
	v_lshlrev_b32_e32 v6, 4, v0
	v_lshrrev_b32_e32 v0, 4, v138
	v_ashrrev_i32_e32 v4, 6, v138
	v_sub_u32_e32 v8, 0, v0
	s_and_b32 s17, s10, 0x3f00
	s_lshl_b32 s10, s15, 1
	v_bfe_u32 v7, v138, 2, 4
	v_xor_b32_e32 v2, v138, v8
	v_lshlrev_b32_e32 v9, 4, v4
	s_load_dwordx16 s[64:79], s[0:1], 0x160
	s_and_b32 s16, s10, 0xffffff80
	v_or_b32_e32 v3, v7, v9
	v_lshlrev_b32_e32 v2, 4, v2
	v_add_u32_e32 v0, s17, v3
	v_and_b32_e32 v134, 48, v2
	v_add_u32_e32 v2, s16, v3
	v_ashrrev_i32_e32 v1, 31, v0
	v_ashrrev_i32_e32 v3, 31, v2
	v_lshlrev_b64 v[0:1], 11, v[0:1]
	v_lshlrev_b64 v[2:3], 11, v[2:3]
	s_waitcnt lgkmcnt(0)
	v_lshl_add_u64 v[0:1], s[30:31], 0, v[0:1]
	v_lshl_add_u64 v[2:3], s[72:73], 0, v[2:3]
	v_lshl_add_u64 v[0:1], v[0:1], 0, v[134:135]
	v_lshl_add_u64 v[2:3], v[2:3], 0, v[134:135]
	v_lshlrev_b32_e32 v134, 10, v4
	v_add_u32_e32 v10, 0x1000, v134
	v_readfirstlane_b32 s10, v134
	s_nop 0
	s_mov_b32 m0, s10
	v_readfirstlane_b32 s10, v10
	v_add_u32_e32 v10, 0x2000, v134
	v_lshl_add_u64 v[4:5], v[0:1], 0, s[96:97]
	s_mov_b32 m0, s10
	v_readfirstlane_b32 s10, v10
	v_lshl_add_u64 v[4:5], v[0:1], 0, s[86:87]
	s_mov_b32 m0, s10
	s_mov_b64 s[10:11], 0x60000
	v_add_u32_e32 v10, 0x3000, v134
	v_lshl_add_u64 v[4:5], v[0:1], 0, s[10:11]
	v_readfirstlane_b32 s10, v10
	s_mov_b32 m0, s10
	v_add_u32_e32 v10, 0x5000, v134
	v_add_u32_e32 v4, 0x4000, v134
	s_mov_b64 s[12:13], 0x20040
	v_readfirstlane_b32 s10, v4
	s_mov_b32 m0, s10
	v_readfirstlane_b32 s10, v10
	v_add_u32_e32 v10, 0x6000, v134
	v_lshl_add_u64 v[4:5], v[2:3], 0, s[96:97]
	s_mov_b32 m0, s10
	v_readfirstlane_b32 s10, v10
	v_add_u32_e32 v10, 0x7000, v134
	v_lshl_add_u64 v[4:5], v[0:1], 0, 64
	s_mov_b32 m0, s10
	v_readfirstlane_b32 s10, v10
	v_lshl_add_u64 v[4:5], v[0:1], 0, s[12:13]
	s_mov_b32 m0, s10
	s_mov_b64 s[10:11], 0x40040
	v_add_u32_e32 v10, 0x8000, v134
	v_lshl_add_u64 v[4:5], v[0:1], 0, s[10:11]
	v_readfirstlane_b32 s10, v10
	s_mov_b32 m0, s10
	s_mov_b64 s[10:11], 0x60040
	v_add_u32_e32 v4, 0x9000, v134
	v_lshl_add_u64 v[0:1], v[0:1], 0, s[10:11]
	v_readfirstlane_b32 s10, v4
	v_add_u32_e32 v4, 0xa000, v134
	s_mov_b32 m0, s10
	v_readfirstlane_b32 s10, v4
	v_lshl_add_u64 v[0:1], v[2:3], 0, 64
	s_mov_b32 m0, s10
	s_and_b32 s6, s4, 0xffffff80
	v_lshl_add_u64 v[0:1], v[2:3], 0, s[12:13]
	v_add_u32_e32 v2, 0xb000, v134
	s_and_b32 s7, s14, 0x3f00
	v_readfirstlane_b32 s10, v2
	s_mov_b32 m0, s10
	v_bitop3_b32 v2, v138, 3, v8 bitop3:0x48
	v_lshlrev_b32_e32 v0, 6, v138
	v_and_or_b32 v143, v0, s80, v6
	v_lshlrev_b32_e32 v0, 1, v138
	v_and_b32_e32 v1, 0x43, v138
	v_and_or_b32 v0, v0, 24, v1
	v_lshrrev_b32_e32 v1, 1, v138
	v_and_b32_e32 v1, 2, v1
	v_sub_u32_e32 v1, 0, v1
	v_bitop3_b32 v1, v1, v140, 2 bitop3:0x6c
	v_lshlrev_b32_e32 v1, 4, v1
	v_lshl_or_b32 v144, v0, 6, v1
	v_or_b32_e32 v0, 4, v0
	v_lshlrev_b32_e32 v1, 6, v0
	v_lshrrev_b32_e32 v0, 2, v0
	v_sub_u32_e32 v0, 0, v0
	v_bitop3_b32 v0, v0, v140, 3 bitop3:0x6c
	v_lshl_or_b32 v145, v0, 4, v1
	v_or_b32_e32 v0, s6, v7
	v_add_u32_e32 v0, v0, v9
	v_ashrrev_i32_e32 v1, 31, v0
	v_lshlrev_b64 v[0:1], 11, v[0:1]
	v_lshlrev_b32_e32 v2, 4, v2
	v_or_b32_e32 v0, v0, v2
	v_lshl_add_u64 v[128:129], s[72:73], 0, v[0:1]
	v_or_b32_e32 v0, s7, v7
	v_add_u32_e32 v0, v0, v9
	v_ashrrev_i32_e32 v1, 31, v0
	s_nop 0
	v_lshlrev_b64 v[0:1], 11, v[0:1]
	s_waitcnt lgkmcnt(0)
; #define WAIT_V(n) asm volatile("s_waitcnt vmcnt(%0)" ::"n"(n) : "memory")
; #define RAW_BARRIER() do { asm volatile("s_waitcnt lgkmcnt(0)" ::: "memory"); __builtin_amdgcn_s_barrier(); } while (0)
; #define DSR(dst, addr, off) asm volatile("ds_read_b128 %0, %1 offset:%2" : "=v"(dst) : "v"(addr), "n"(off) : "memory")
; __device__ __forceinline__ void gb_step(const u16* ga, const u16* gw, size_t a64, size_t w64, int ko, bool issue, ...
;     ...
;   const unsigned rdb = (unsigned)(size_t)(__attribute__((address_space(3))) const char*)rd;
;   const unsigned ab = rdb + (unsigned)(((wm * 128 + (lane & 15)) * GST + rsw) * 2);
;   const int wr0 = wn * 64 + (((lane & 15) >> 2) << 3) + (lane & 3);
;   const unsigned bb0 = rdb + (unsigned)((256 * GST + wr0 * GST + GSW(wr0, lane >> 4)) * 2);
;   const unsigned bb1 = rdb + (unsigned)((256 * GST + (wr0 + 4) * GST + GSW(wr0 + 4, lane >> 4)) * 2);
;   bf16x8 wf0, wf1, wf2, wf3, xf0, xf1, xf2, xf3, xf4, xf5, xf6, xf7;
;     ...
;   DSR(wf0, bb0, 0); DSR(wf1, bb1, 0); DSR(wf2, bb0, 2048); DSR(wf3, bb1, 2048);
;   DSR(xf0, ab, 0); DSR(xf1, ab, 1024); DSR(xf2, ab, 2048); DSR(xf3, ab, 3072);
;   DSR(xf4, ab, 4096); DSR(xf5, ab, 5120); DSR(xf6, ab, 6144); DSR(xf7, ab, 7168);
; template <class F>
; __device__ __forceinline__ void gemm_big(const ALbf& al, const u16* __restrict__ Wt, int K, int m0, int n0, const F& f, u16* sm) {
;     ...
;   f32x4 acc[4][8];
; #pragma unroll
;   for (int i = 0; i < 4; i++)
; #pragma unroll
;     for (int j = 0; j < 8; j++) acc[i][j] = (f32x4){0.f, 0.f, 0.f, 0.f};
;   const int srow = lane >> 2;
;   const int scol = ((lane & 3) ^ ((0 - (srow >> 2)) & 3)) * 8;
;   const u16* ga = al.A + (size_t)(m0 + wave * 16 + srow) * al.lda + scol;
;   const u16* gw = Wt + (size_t)(n0 + wave * 16 + srow) * K + scol;
;   const size_t a64 = (size_t)64 * al.lda, w64 = (size_t)64 * K;
;   const int nk = K >> 5;
;   WAIT_V(0);
;   gb_issue(ga, gw, a64, w64, 0, sm, wave);
;   gb_issue(ga, gw, a64, w64, 32, sm + GB_STAGE_EL, wave);
;   WAIT_V(6);
;   RAW_BARRIER();
	v_or_b32_e32 v0, v0, v2
	v_lshl_add_u64 v[130:131], s[30:31], 0, v[0:1]
	v_mov_b32_e32 v0, 0
	s_mov_b32 s60, 0
	s_mov_b64 s[6:7], 0
	s_mov_b32 s61, 0
	v_mov_b32_e32 v1, v0
	v_mov_b32_e32 v2, v0
	v_mov_b32_e32 v3, v0
	v_mov_b32_e32 v4, v0
	v_mov_b32_e32 v5, v0
	v_mov_b32_e32 v6, v0
	v_mov_b32_e32 v7, v0
	v_mov_b32_e32 v32, v0
	v_mov_b32_e32 v33, v0
	v_mov_b32_e32 v34, v0
	v_mov_b32_e32 v35, v0
	v_mov_b32_e32 v36, v0
	v_mov_b32_e32 v37, v0
	v_mov_b32_e32 v38, v0
	v_mov_b32_e32 v39, v0
	v_mov_b32_e32 v8, v0
	v_mov_b32_e32 v9, v0
	v_mov_b32_e32 v10, v0
	v_mov_b32_e32 v11, v0
	v_mov_b32_e32 v12, v0
	v_mov_b32_e32 v13, v0
	v_mov_b32_e32 v14, v0
	v_mov_b32_e32 v15, v0
	v_mov_b32_e32 v48, v0
	v_mov_b32_e32 v49, v0
	v_mov_b32_e32 v50, v0
	v_mov_b32_e32 v51, v0
	v_mov_b32_e32 v52, v0
	v_mov_b32_e32 v53, v0
	v_mov_b32_e32 v54, v0
	v_mov_b32_e32 v55, v0
	v_mov_b32_e32 v16, v0
	v_mov_b32_e32 v17, v0
	v_mov_b32_e32 v18, v0
	v_mov_b32_e32 v19, v0
	v_mov_b32_e32 v20, v0
	v_mov_b32_e32 v21, v0
	v_mov_b32_e32 v22, v0
	v_mov_b32_e32 v23, v0
	v_mov_b32_e32 v64, v0
	v_mov_b32_e32 v65, v0
	v_mov_b32_e32 v66, v0
	v_mov_b32_e32 v67, v0
	v_mov_b32_e32 v72, v0
	v_mov_b32_e32 v73, v0
	v_mov_b32_e32 v74, v0
	v_mov_b32_e32 v75, v0
	v_mov_b32_e32 v24, v0
	v_mov_b32_e32 v25, v0
	v_mov_b32_e32 v26, v0
	v_mov_b32_e32 v27, v0
	v_mov_b32_e32 v28, v0
	v_mov_b32_e32 v29, v0
	v_mov_b32_e32 v30, v0
	v_mov_b32_e32 v31, v0
	v_mov_b32_e32 v88, v0
	v_mov_b32_e32 v89, v0
	v_mov_b32_e32 v90, v0
	v_mov_b32_e32 v91, v0
	v_mov_b32_e32 v92, v0
	v_mov_b32_e32 v93, v0
	v_mov_b32_e32 v94, v0
	v_mov_b32_e32 v95, v0
	v_mov_b32_e32 v40, v0
	v_mov_b32_e32 v41, v0
	v_mov_b32_e32 v42, v0
	v_mov_b32_e32 v43, v0
	v_mov_b32_e32 v44, v0
	v_mov_b32_e32 v45, v0
	v_mov_b32_e32 v46, v0
	v_mov_b32_e32 v47, v0
	v_mov_b32_e32 v96, v0
	v_mov_b32_e32 v97, v0
	v_mov_b32_e32 v98, v0
	v_mov_b32_e32 v99, v0
	v_mov_b32_e32 v100, v0
	v_mov_b32_e32 v101, v0
	v_mov_b32_e32 v102, v0
	v_mov_b32_e32 v103, v0
	v_mov_b32_e32 v56, v0
	v_mov_b32_e32 v57, v0
	v_mov_b32_e32 v58, v0
	v_mov_b32_e32 v59, v0
	v_mov_b32_e32 v60, v0
	v_mov_b32_e32 v61, v0
	v_mov_b32_e32 v62, v0
	v_mov_b32_e32 v63, v0
	v_mov_b32_e32 v104, v0
	v_mov_b32_e32 v105, v0
	v_mov_b32_e32 v106, v0
	v_mov_b32_e32 v107, v0
	v_mov_b32_e32 v108, v0
	v_mov_b32_e32 v109, v0
	v_mov_b32_e32 v110, v0
	v_mov_b32_e32 v111, v0
	v_mov_b32_e32 v68, v0
	v_mov_b32_e32 v69, v0
	v_mov_b32_e32 v70, v0
	v_mov_b32_e32 v71, v0
	v_mov_b32_e32 v76, v0
	v_mov_b32_e32 v77, v0
	v_mov_b32_e32 v78, v0
	v_mov_b32_e32 v79, v0
	v_mov_b32_e32 v112, v0
	v_mov_b32_e32 v113, v0
	v_mov_b32_e32 v114, v0
	v_mov_b32_e32 v115, v0
	v_mov_b32_e32 v116, v0
	v_mov_b32_e32 v117, v0
	v_mov_b32_e32 v118, v0
	v_mov_b32_e32 v119, v0
	v_mov_b32_e32 v80, v0
	v_mov_b32_e32 v81, v0
	v_mov_b32_e32 v82, v0
	v_mov_b32_e32 v83, v0
	v_mov_b32_e32 v84, v0
	v_mov_b32_e32 v85, v0
	v_mov_b32_e32 v86, v0
	v_mov_b32_e32 v87, v0
	v_mov_b32_e32 v120, v0
	v_mov_b32_e32 v121, v0
	v_mov_b32_e32 v122, v0
	v_mov_b32_e32 v123, v0
	v_mov_b32_e32 v124, v0
	v_mov_b32_e32 v125, v0
	v_mov_b32_e32 v126, v0
	v_mov_b32_e32 v127, v0
	v_readfirstlane_b32 s6, v130
	v_readfirstlane_b32 s7, v131
	v_readfirstlane_b32 s10, v128
	v_readfirstlane_b32 s11, v129
	v_readfirstlane_b32 s61, v134
	v_and_b32_e32 v176, 63, v132
	v_lshrrev_b32_e32 v177, 6, v132
	v_lshrrev_b32_e32 v178, 3, v176
	v_and_b32_e32 v179, 7, v176
	v_lshrrev_b32_e32 v180, 4, v176
	v_and_b32_e32 v181, 1, v177
	v_lshrrev_b32_e32 v182, 1, v177
	v_lshl_add_u32 v183, v181, 2, v180
	v_xor_b32_e32 v183, v179, v183
	v_lshl_add_u32 v184, v177, 3, v178
	v_lshlrev_b32_e32 v188, 11, v184
	v_lshl_add_u32 v128, v183, 4, v188
	v_add_u32_e32 v129, 0x10000, v128
	v_add_u32_e32 v130, 0x40000, v128
	v_add_u32_e32 v131, 0x50000, v128
	v_bfe_u32 v185, v178, 1, 1
	v_lshl_or_b32 v185, v181, 1, v185
	v_lshl_or_b32 v185, v182, 2, v185
	v_xor_b32_e32 v185, v179, v185
	v_lshl_add_u32 v134, v185, 4, v188
	v_add_u32_e32 v143, 0x10000, v134
	v_add_u32_e32 v196, 0x20000, v134
	v_add_u32_e32 v197, 0x30000, v134
	v_and_b32_e32 v186, 15, v176
	v_bfe_u32 v187, v176, 1, 3
	v_xor_b32_e32 v187, v180, v187
	v_lshlrev_b32_e32 v187, 4, v187
	v_lshl_add_u32 v188, v182, 6, v186
	v_lshl_add_u32 v219, v188, 7, v187
	v_xor_b32_e32 v228, 64, v219
	v_lshrrev_b32_e32 v189, 2, v186
	v_lshlrev_b32_e32 v189, 3, v189
	v_and_b32_e32 v188, 3, v186
	v_add_u32_e32 v189, v189, v188
	v_lshl_add_u32 v189, v181, 6, v189
	v_lshl_add_u32 v231, v189, 7, v187
	v_xor_b32_e32 v216, 64, v231
	s_lshl_b32 s13, s61, 5
	s_sub_u32 s6, s6, s13
	s_subb_u32 s7, s7, 0
	s_sub_u32 s10, s10, s13
	s_subb_u32 s11, s11, 0
	s_add_u32 m0, s61, 0x8000
	s_nop 0
	global_load_lds_dwordx4 v128, s[6:7]
	s_add_u32 m0, s61, 0x9000
	s_nop 0
	global_load_lds_dwordx4 v129, s[6:7]
	s_add_u32 m0, s61, 0xa000
	s_nop 0
	global_load_lds_dwordx4 v130, s[6:7]
	s_add_u32 m0, s61, 0xb000
	s_nop 0
	global_load_lds_dwordx4 v131, s[6:7]
	s_add_u32 s6, s6, 0x20000
	s_addc_u32 s7, s7, 0
	s_add_u32 m0, s61, 0xc000
	s_nop 0
	global_load_lds_dwordx4 v128, s[6:7]
	s_add_u32 m0, s61, 0xd000
	s_nop 0
	global_load_lds_dwordx4 v129, s[6:7]
	s_add_u32 m0, s61, 0xe000
	s_nop 0
	global_load_lds_dwordx4 v130, s[6:7]
	s_add_u32 m0, s61, 0xf000
	s_nop 0
	global_load_lds_dwordx4 v131, s[6:7]
	s_add_u32 s6, s6, 0xfffe0080
	s_addc_u32 s7, s7, -1
	s_add_u32 m0, s61, 0x0
	s_nop 0
	global_load_lds_dwordx4 v134, s[10:11]
	s_add_u32 m0, s61, 0x1000
	s_nop 0
	global_load_lds_dwordx4 v143, s[10:11]
	s_add_u32 m0, s61, 0x2000
	s_nop 0
	global_load_lds_dwordx4 v196, s[10:11]
	s_add_u32 m0, s61, 0x3000
	s_nop 0
	global_load_lds_dwordx4 v197, s[10:11]
	s_add_u32 s10, s10, 0x80
	s_addc_u32 s11, s11, 0
	s_add_u32 m0, s61, 0x4000
	s_nop 0
	global_load_lds_dwordx4 v134, s[10:11]
	s_add_u32 m0, s61, 0x5000
	s_nop 0
	global_load_lds_dwordx4 v143, s[10:11]
	s_add_u32 m0, s61, 0x6000
	s_nop 0
	global_load_lds_dwordx4 v196, s[10:11]
	s_add_u32 m0, s61, 0x7000
	s_nop 0
	global_load_lds_dwordx4 v197, s[10:11]
	s_add_u32 s10, s10, 0x80
	s_addc_u32 s11, s11, 0
	s_waitcnt vmcnt(0)
	s_barrier
	s_mov_b32 s12, 0
	s_mov_b32 s60, 0
	ds_read_b128 v[144:147], v219 offset:32768
	ds_read_b128 v[148:151], v219 offset:34816
	ds_read_b128 v[152:155], v219 offset:36864
	ds_read_b128 v[156:159], v219 offset:38912
	ds_read_b128 v[160:163], v228 offset:32768
	ds_read_b128 v[164:167], v228 offset:34816
	ds_read_b128 v[168:171], v228 offset:36864
	ds_read_b128 v[172:175], v228 offset:38912
	v_add_u32_e32 v248, s12, v231
	ds_read_b128 v[236:239], v248 offset:0
	ds_read_b128 v[240:243], v248 offset:512
	ds_read_b128 v[244:247], v248 offset:4096
	ds_read_b128 v[248:251], v248 offset:4608
	s_waitcnt lgkmcnt(0)
	s_barrier

; __device__ __forceinline__ int ltid() { int t = threadIdx.x; asm volatile("" : "+v"(t)); return t; }
; #define WAIT_V(n) asm volatile("s_waitcnt vmcnt(%0)" ::"n"(n) : "memory")
; template <class F>
; __device__ __forceinline__ void gemm_big(const ALbf& al, const u16* __restrict__ Wt, int K, int m0, int n0, const F& f, u16* sm) {
;   const int tid = ltid(), lane = tid & 63, wave = tid >> 6;
;   const int wm = wave >> 1, wn = wave & 1;
;   const int rsw = GSW(lane & 15, lane >> 4);
;   f32x4 acc[4][8];
; #pragma unroll
;   for (int i = 0; i < 4; i++)
; #pragma unroll
;     for (int j = 0; j < 8; j++) acc[i][j] = (f32x4){0.f, 0.f, 0.f, 0.f};
;   const int srow = lane >> 2;
;   const int scol = ((lane & 3) ^ ((0 - (srow >> 2)) & 3)) * 8;
;   const u16* ga = al.A + (size_t)(m0 + wave * 16 + srow) * al.lda + scol;
;   const u16* gw = Wt + (size_t)(n0 + wave * 16 + srow) * K + scol;
;   const size_t a64 = (size_t)64 * al.lda, w64 = (size_t)64 * K;
;   const int nk = K >> 5;
;   WAIT_V(0);
;   gb_issue(ga, gw, a64, w64, 0, sm, wave);
.LBB0_279:
	v_mov_b32_e32 v138, v132
	s_lshl_b32 s8, s13, 8
	v_lshrrev_b32_e32 v0, 2, v138
	v_bfe_u32 v140, v138, 4, 2
	v_sub_u32_e32 v0, 0, v0
	v_bitop3_b32 v0, v140, v0, 3 bitop3:0x78
	v_lshlrev_b32_e32 v6, 4, v0
	v_lshrrev_b32_e32 v0, 4, v138
	v_ashrrev_i32_e32 v4, 6, v138
	v_sub_u32_e32 v8, 0, v0
	s_and_b32 s15, s8, 0x3f00
	s_lshl_b32 s8, s13, 1
	v_bfe_u32 v7, v138, 2, 4
	v_xor_b32_e32 v2, v138, v8
	v_lshlrev_b32_e32 v9, 4, v4
	s_load_dwordx16 s[60:75], s[0:1], 0x160
	s_and_b32 s14, s8, 0xffffff80
	v_or_b32_e32 v3, v7, v9
	v_lshlrev_b32_e32 v2, 4, v2
	v_add_u32_e32 v0, s15, v3
	v_and_b32_e32 v134, 48, v2
	v_add_u32_e32 v2, s14, v3
	v_ashrrev_i32_e32 v1, 31, v0
	v_ashrrev_i32_e32 v3, 31, v2
	v_lshlrev_b64 v[0:1], 11, v[0:1]
	v_lshlrev_b64 v[2:3], 11, v[2:3]
	s_waitcnt lgkmcnt(0)
	v_lshl_add_u64 v[0:1], s[30:31], 0, v[0:1]
	v_lshl_add_u64 v[2:3], s[62:63], 0, v[2:3]
	v_lshl_add_u64 v[0:1], v[0:1], 0, v[134:135]
	v_lshl_add_u64 v[2:3], v[2:3], 0, v[134:135]
	v_lshlrev_b32_e32 v134, 10, v4
	v_add_u32_e32 v10, 0x1000, v134
	v_readfirstlane_b32 s8, v134
	s_nop 0
	s_mov_b32 m0, s8
	v_readfirstlane_b32 s8, v10
	v_add_u32_e32 v10, 0x2000, v134
	v_lshl_add_u64 v[4:5], v[0:1], 0, s[96:97]
	s_mov_b32 m0, s8
	v_readfirstlane_b32 s8, v10
	v_lshl_add_u64 v[4:5], v[0:1], 0, s[86:87]
	s_mov_b32 m0, s8
	s_mov_b64 s[8:9], 0x60000
	v_add_u32_e32 v10, 0x3000, v134
	v_lshl_add_u64 v[4:5], v[0:1], 0, s[8:9]
	v_readfirstlane_b32 s8, v10
	s_mov_b32 m0, s8
	v_add_u32_e32 v10, 0x5000, v134
	v_add_u32_e32 v4, 0x4000, v134
	s_mov_b64 s[10:11], 0x20040
	v_readfirstlane_b32 s8, v4
	s_mov_b32 m0, s8
	v_readfirstlane_b32 s8, v10
	v_add_u32_e32 v10, 0x6000, v134
	v_lshl_add_u64 v[4:5], v[2:3], 0, s[96:97]
	s_mov_b32 m0, s8
	v_readfirstlane_b32 s8, v10
	v_add_u32_e32 v10, 0x7000, v134
	v_lshl_add_u64 v[4:5], v[0:1], 0, 64
	s_mov_b32 m0, s8
	v_readfirstlane_b32 s8, v10
	v_lshl_add_u64 v[4:5], v[0:1], 0, s[10:11]
	s_mov_b32 m0, s8
	s_mov_b64 s[8:9], 0x40040
	v_add_u32_e32 v10, 0x8000, v134
	v_lshl_add_u64 v[4:5], v[0:1], 0, s[8:9]
	v_readfirstlane_b32 s8, v10
	s_mov_b32 m0, s8
	s_mov_b64 s[8:9], 0x60040
	v_add_u32_e32 v4, 0x9000, v134
	v_lshl_add_u64 v[0:1], v[0:1], 0, s[8:9]
	v_readfirstlane_b32 s8, v4
	v_add_u32_e32 v4, 0xa000, v134
	s_mov_b32 m0, s8
	v_readfirstlane_b32 s8, v4
	v_lshl_add_u64 v[0:1], v[2:3], 0, 64
	s_mov_b32 m0, s8
	s_and_b32 s6, s4, 0xffffff80
	v_lshl_add_u64 v[0:1], v[2:3], 0, s[10:11]
	v_add_u32_e32 v2, 0xb000, v134
	s_and_b32 s7, s12, 0x3f00
	v_readfirstlane_b32 s8, v2
	s_mov_b32 m0, s8
	v_bitop3_b32 v2, v138, 3, v8 bitop3:0x48
	v_lshlrev_b32_e32 v0, 6, v138
	v_and_or_b32 v143, v0, s80, v6
	v_lshlrev_b32_e32 v0, 1, v138
	v_and_b32_e32 v1, 0x43, v138
	v_and_or_b32 v0, v0, 24, v1
	v_lshrrev_b32_e32 v1, 1, v138
	v_and_b32_e32 v1, 2, v1
	v_sub_u32_e32 v1, 0, v1
	v_bitop3_b32 v1, v1, v140, 2 bitop3:0x6c
	v_lshlrev_b32_e32 v1, 4, v1
	v_lshl_or_b32 v144, v0, 6, v1
	v_or_b32_e32 v0, 4, v0
	v_lshlrev_b32_e32 v1, 6, v0
	v_lshrrev_b32_e32 v0, 2, v0
	v_sub_u32_e32 v0, 0, v0
	v_bitop3_b32 v0, v0, v140, 3 bitop3:0x6c
	v_lshl_or_b32 v145, v0, 4, v1
	v_or_b32_e32 v0, s6, v7
	v_add_u32_e32 v0, v0, v9
	v_ashrrev_i32_e32 v1, 31, v0
	v_lshlrev_b64 v[0:1], 11, v[0:1]
	v_lshlrev_b32_e32 v2, 4, v2
	v_or_b32_e32 v0, v0, v2
	v_lshl_add_u64 v[128:129], s[62:63], 0, v[0:1]
	v_or_b32_e32 v0, s7, v7
	v_add_u32_e32 v0, v0, v9
	v_ashrrev_i32_e32 v1, 31, v0
	s_nop 0
	v_lshlrev_b64 v[0:1], 11, v[0:1]
	s_waitcnt lgkmcnt(0)
; #define WAIT_V(n) asm volatile("s_waitcnt vmcnt(%0)" ::"n"(n) : "memory")
; #define RAW_BARRIER() do { asm volatile("s_waitcnt lgkmcnt(0)" ::: "memory"); __builtin_amdgcn_s_barrier(); } while (0)
; #define DSR(dst, addr, off) asm volatile("ds_read_b128 %0, %1 offset:%2" : "=v"(dst) : "v"(addr), "n"(off) : "memory")
; __device__ __forceinline__ void gb_step(const u16* ga, const u16* gw, size_t a64, size_t w64, int ko, bool issue, ...
;     ...
;   const unsigned rdb = (unsigned)(size_t)(__attribute__((address_space(3))) const char*)rd;
;   const unsigned ab = rdb + (unsigned)(((wm * 128 + (lane & 15)) * GST + rsw) * 2);
;   const int wr0 = wn * 64 + (((lane & 15) >> 2) << 3) + (lane & 3);
;   const unsigned bb0 = rdb + (unsigned)((256 * GST + wr0 * GST + GSW(wr0, lane >> 4)) * 2);
;   const unsigned bb1 = rdb + (unsigned)((256 * GST + (wr0 + 4) * GST + GSW(wr0 + 4, lane >> 4)) * 2);
;   bf16x8 wf0, wf1, wf2, wf3, xf0, xf1, xf2, xf3, xf4, xf5, xf6, xf7;
;     ...
;   DSR(wf0, bb0, 0); DSR(wf1, bb1, 0); DSR(wf2, bb0, 2048); DSR(wf3, bb1, 2048);
;   DSR(xf0, ab, 0); DSR(xf1, ab, 1024); DSR(xf2, ab, 2048); DSR(xf3, ab, 3072);
;   DSR(xf4, ab, 4096); DSR(xf5, ab, 5120); DSR(xf6, ab, 6144); DSR(xf7, ab, 7168);
; template <class F>
; __device__ __forceinline__ void gemm_big(const ALbf& al, const u16* __restrict__ Wt, int K, int m0, int n0, const F& f, u16* sm) {
;     ...
;   f32x4 acc[4][8];
; #pragma unroll
;   for (int i = 0; i < 4; i++)
; #pragma unroll
;     for (int j = 0; j < 8; j++) acc[i][j] = (f32x4){0.f, 0.f, 0.f, 0.f};
;   const int srow = lane >> 2;
;   const int scol = ((lane & 3) ^ ((0 - (srow >> 2)) & 3)) * 8;
;   const u16* ga = al.A + (size_t)(m0 + wave * 16 + srow) * al.lda + scol;
;   const u16* gw = Wt + (size_t)(n0 + wave * 16 + srow) * K + scol;
;   const size_t a64 = (size_t)64 * al.lda, w64 = (size_t)64 * K;
;   const int nk = K >> 5;
;   WAIT_V(0);
;   gb_issue(ga, gw, a64, w64, 0, sm, wave);
;   gb_issue(ga, gw, a64, w64, 32, sm + GB_STAGE_EL, wave);
;   WAIT_V(6);
;   RAW_BARRIER();
	v_or_b32_e32 v0, v0, v2
	v_lshl_add_u64 v[130:131], s[30:31], 0, v[0:1]
	v_mov_b32_e32 v0, 0
	s_mov_b32 s16, 0
	s_mov_b64 s[6:7], 0
	s_mov_b32 s17, 0
	v_mov_b32_e32 v1, v0
	v_mov_b32_e32 v2, v0
	v_mov_b32_e32 v3, v0
	v_mov_b32_e32 v4, v0
	v_mov_b32_e32 v5, v0
	v_mov_b32_e32 v6, v0
	v_mov_b32_e32 v7, v0
	v_mov_b32_e32 v32, v0
	v_mov_b32_e32 v33, v0
	v_mov_b32_e32 v34, v0
	v_mov_b32_e32 v35, v0
	v_mov_b32_e32 v36, v0
	v_mov_b32_e32 v37, v0
	v_mov_b32_e32 v38, v0
	v_mov_b32_e32 v39, v0
	v_mov_b32_e32 v8, v0
	v_mov_b32_e32 v9, v0
	v_mov_b32_e32 v10, v0
	v_mov_b32_e32 v11, v0
	v_mov_b32_e32 v12, v0
	v_mov_b32_e32 v13, v0
	v_mov_b32_e32 v14, v0
	v_mov_b32_e32 v15, v0
	v_mov_b32_e32 v48, v0
	v_mov_b32_e32 v49, v0
	v_mov_b32_e32 v50, v0
	v_mov_b32_e32 v51, v0
	v_mov_b32_e32 v52, v0
	v_mov_b32_e32 v53, v0
	v_mov_b32_e32 v54, v0
	v_mov_b32_e32 v55, v0
	v_mov_b32_e32 v16, v0
	v_mov_b32_e32 v17, v0
	v_mov_b32_e32 v18, v0
	v_mov_b32_e32 v19, v0
	v_mov_b32_e32 v20, v0
	v_mov_b32_e32 v21, v0
	v_mov_b32_e32 v22, v0
	v_mov_b32_e32 v23, v0
	v_mov_b32_e32 v64, v0
	v_mov_b32_e32 v65, v0
	v_mov_b32_e32 v66, v0
	v_mov_b32_e32 v67, v0
	v_mov_b32_e32 v72, v0
	v_mov_b32_e32 v73, v0
	v_mov_b32_e32 v74, v0
	v_mov_b32_e32 v75, v0
	v_mov_b32_e32 v24, v0
	v_mov_b32_e32 v25, v0
	v_mov_b32_e32 v26, v0
	v_mov_b32_e32 v27, v0
	v_mov_b32_e32 v28, v0
	v_mov_b32_e32 v29, v0
	v_mov_b32_e32 v30, v0
	v_mov_b32_e32 v31, v0
	v_mov_b32_e32 v88, v0
	v_mov_b32_e32 v89, v0
	v_mov_b32_e32 v90, v0
	v_mov_b32_e32 v91, v0
	v_mov_b32_e32 v92, v0
	v_mov_b32_e32 v93, v0
	v_mov_b32_e32 v94, v0
	v_mov_b32_e32 v95, v0
	v_mov_b32_e32 v40, v0
	v_mov_b32_e32 v41, v0
	v_mov_b32_e32 v42, v0
	v_mov_b32_e32 v43, v0
	v_mov_b32_e32 v44, v0
	v_mov_b32_e32 v45, v0
	v_mov_b32_e32 v46, v0
	v_mov_b32_e32 v47, v0
	v_mov_b32_e32 v96, v0
	v_mov_b32_e32 v97, v0
	v_mov_b32_e32 v98, v0
	v_mov_b32_e32 v99, v0
	v_mov_b32_e32 v100, v0
	v_mov_b32_e32 v101, v0
	v_mov_b32_e32 v102, v0
	v_mov_b32_e32 v103, v0
	v_mov_b32_e32 v56, v0
	v_mov_b32_e32 v57, v0
	v_mov_b32_e32 v58, v0
	v_mov_b32_e32 v59, v0
	v_mov_b32_e32 v60, v0
	v_mov_b32_e32 v61, v0
	v_mov_b32_e32 v62, v0
	v_mov_b32_e32 v63, v0
	v_mov_b32_e32 v104, v0
	v_mov_b32_e32 v105, v0
	v_mov_b32_e32 v106, v0
	v_mov_b32_e32 v107, v0
	v_mov_b32_e32 v108, v0
	v_mov_b32_e32 v109, v0
	v_mov_b32_e32 v110, v0
	v_mov_b32_e32 v111, v0
	v_mov_b32_e32 v68, v0
	v_mov_b32_e32 v69, v0
	v_mov_b32_e32 v70, v0
	v_mov_b32_e32 v71, v0
	v_mov_b32_e32 v76, v0
	v_mov_b32_e32 v77, v0
	v_mov_b32_e32 v78, v0
	v_mov_b32_e32 v79, v0
	v_mov_b32_e32 v112, v0
	v_mov_b32_e32 v113, v0
	v_mov_b32_e32 v114, v0
	v_mov_b32_e32 v115, v0
	v_mov_b32_e32 v116, v0
	v_mov_b32_e32 v117, v0
	v_mov_b32_e32 v118, v0
	v_mov_b32_e32 v119, v0
	v_mov_b32_e32 v80, v0
	v_mov_b32_e32 v81, v0
	v_mov_b32_e32 v82, v0
	v_mov_b32_e32 v83, v0
	v_mov_b32_e32 v84, v0
	v_mov_b32_e32 v85, v0
	v_mov_b32_e32 v86, v0
	v_mov_b32_e32 v87, v0
	v_mov_b32_e32 v120, v0
	v_mov_b32_e32 v121, v0
	v_mov_b32_e32 v122, v0
	v_mov_b32_e32 v123, v0
	v_mov_b32_e32 v124, v0
	v_mov_b32_e32 v125, v0
	v_mov_b32_e32 v126, v0
	v_mov_b32_e32 v127, v0
	v_readfirstlane_b32 s6, v130
	v_readfirstlane_b32 s7, v131
	v_readfirstlane_b32 s8, v128
	v_readfirstlane_b32 s9, v129
	v_readfirstlane_b32 s17, v134
	v_and_b32_e32 v176, 63, v132
	v_lshrrev_b32_e32 v177, 6, v132
	v_lshrrev_b32_e32 v178, 3, v176
	v_and_b32_e32 v179, 7, v176
	v_lshrrev_b32_e32 v180, 4, v176
	v_and_b32_e32 v181, 1, v177
	v_lshrrev_b32_e32 v182, 1, v177
	v_lshl_add_u32 v183, v181, 2, v180
	v_xor_b32_e32 v183, v179, v183
	v_lshl_add_u32 v184, v177, 3, v178
	v_lshlrev_b32_e32 v188, 11, v184
	v_lshl_add_u32 v128, v183, 4, v188
	v_add_u32_e32 v129, 0x10000, v128
	v_add_u32_e32 v130, 0x40000, v128
	v_add_u32_e32 v131, 0x50000, v128
	v_bfe_u32 v185, v178, 1, 1
	v_lshl_or_b32 v185, v181, 1, v185
	v_lshl_or_b32 v185, v182, 2, v185
	v_xor_b32_e32 v185, v179, v185
	v_lshl_add_u32 v134, v185, 4, v188
	v_add_u32_e32 v143, 0x10000, v134
	v_add_u32_e32 v196, 0x20000, v134
	v_add_u32_e32 v197, 0x30000, v134
	v_and_b32_e32 v186, 15, v176
	v_bfe_u32 v187, v176, 1, 3
	v_xor_b32_e32 v187, v180, v187
	v_lshlrev_b32_e32 v187, 4, v187
	v_lshl_add_u32 v188, v182, 6, v186
	v_lshl_add_u32 v219, v188, 7, v187
	v_xor_b32_e32 v228, 64, v219
	v_lshrrev_b32_e32 v189, 2, v186
	v_lshlrev_b32_e32 v189, 3, v189
	v_and_b32_e32 v188, 3, v186
	v_add_u32_e32 v189, v189, v188
	v_lshl_add_u32 v189, v181, 6, v189
	v_lshl_add_u32 v231, v189, 7, v187
	v_xor_b32_e32 v216, 64, v231
	s_lshl_b32 s11, s17, 5
	s_sub_u32 s6, s6, s11
	s_subb_u32 s7, s7, 0
	s_sub_u32 s8, s8, s11
	s_subb_u32 s9, s9, 0
	s_add_u32 m0, s17, 0x8000
	s_nop 0
	global_load_lds_dwordx4 v128, s[6:7]
	s_add_u32 m0, s17, 0x9000
	s_nop 0
	global_load_lds_dwordx4 v129, s[6:7]
	s_add_u32 m0, s17, 0xa000
	s_nop 0
	global_load_lds_dwordx4 v130, s[6:7]
	s_add_u32 m0, s17, 0xb000
	s_nop 0
	global_load_lds_dwordx4 v131, s[6:7]
	s_add_u32 s6, s6, 0x20000
	s_addc_u32 s7, s7, 0
	s_add_u32 m0, s17, 0xc000
	s_nop 0
	global_load_lds_dwordx4 v128, s[6:7]
	s_add_u32 m0, s17, 0xd000
	s_nop 0
	global_load_lds_dwordx4 v129, s[6:7]
	s_add_u32 m0, s17, 0xe000
	s_nop 0
	global_load_lds_dwordx4 v130, s[6:7]
	s_add_u32 m0, s17, 0xf000
	s_nop 0
	global_load_lds_dwordx4 v131, s[6:7]
	s_add_u32 s6, s6, 0xfffe0080
	s_addc_u32 s7, s7, -1
	s_add_u32 m0, s17, 0x0
	s_nop 0
	global_load_lds_dwordx4 v134, s[8:9]
	s_add_u32 m0, s17, 0x1000
	s_nop 0
	global_load_lds_dwordx4 v143, s[8:9]
	s_add_u32 m0, s17, 0x2000
	s_nop 0
	global_load_lds_dwordx4 v196, s[8:9]
	s_add_u32 m0, s17, 0x3000
	s_nop 0
	global_load_lds_dwordx4 v197, s[8:9]
	s_add_u32 s8, s8, 0x80
	s_addc_u32 s9, s9, 0
	s_add_u32 m0, s17, 0x4000
	s_nop 0
	global_load_lds_dwordx4 v134, s[8:9]
	s_add_u32 m0, s17, 0x5000
	s_nop 0
	global_load_lds_dwordx4 v143, s[8:9]
	s_add_u32 m0, s17, 0x6000
	s_nop 0
	global_load_lds_dwordx4 v196, s[8:9]
	s_add_u32 m0, s17, 0x7000
	s_nop 0
	global_load_lds_dwordx4 v197, s[8:9]
	s_add_u32 s8, s8, 0x80
	s_addc_u32 s9, s9, 0
	s_waitcnt vmcnt(0)
	s_barrier
	s_mov_b32 s10, 0
	s_mov_b32 s16, 0
	ds_read_b128 v[144:147], v219 offset:32768
	ds_read_b128 v[148:151], v219 offset:34816
	ds_read_b128 v[152:155], v219 offset:36864
	ds_read_b128 v[156:159], v219 offset:38912
	ds_read_b128 v[160:163], v228 offset:32768
	ds_read_b128 v[164:167], v228 offset:34816
	ds_read_b128 v[168:171], v228 offset:36864
	ds_read_b128 v[172:175], v228 offset:38912
	v_add_u32_e32 v248, s10, v231
	ds_read_b128 v[236:239], v248 offset:0
	ds_read_b128 v[240:243], v248 offset:512
	ds_read_b128 v[244:247], v248 offset:4096
	ds_read_b128 v[248:251], v248 offset:4608
	s_waitcnt lgkmcnt(0)
	s_barrier

; __device__ __forceinline__ int ltid() { int t = threadIdx.x; asm volatile("" : "+v"(t)); return t; }
; #define WAIT_V(n) asm volatile("s_waitcnt vmcnt(%0)" ::"n"(n) : "memory")
; template <class F>
; __device__ __forceinline__ void gemm_big(const ALbf& al, const u16* __restrict__ Wt, int K, int m0, int n0, const F& f, u16* sm) {
;   const int tid = ltid(), lane = tid & 63, wave = tid >> 6;
;   const int wm = wave >> 1, wn = wave & 1;
;   const int rsw = GSW(lane & 15, lane >> 4);
;   f32x4 acc[4][8];
; #pragma unroll
;   for (int i = 0; i < 4; i++)
; #pragma unroll
;     for (int j = 0; j < 8; j++) acc[i][j] = (f32x4){0.f, 0.f, 0.f, 0.f};
;   const int srow = lane >> 2;
;   const int scol = ((lane & 3) ^ ((0 - (srow >> 2)) & 3)) * 8;
;   const u16* ga = al.A + (size_t)(m0 + wave * 16 + srow) * al.lda + scol;
;   const u16* gw = Wt + (size_t)(n0 + wave * 16 + srow) * K + scol;
;   const size_t a64 = (size_t)64 * al.lda, w64 = (size_t)64 * K;
;   const int nk = K >> 5;
;   WAIT_V(0);
;   gb_issue(ga, gw, a64, w64, 0, sm, wave);
.LBB0_322:
	v_mov_b32_e32 v138, v132
	s_lshl_b32 s14, s59, 8
	v_lshrrev_b32_e32 v0, 2, v138
	v_bfe_u32 v140, v138, 4, 2
	v_sub_u32_e32 v0, 0, v0
	v_bitop3_b32 v0, v140, v0, 3 bitop3:0x78
	v_lshlrev_b32_e32 v6, 4, v0
	v_lshrrev_b32_e32 v0, 4, v138
	v_ashrrev_i32_e32 v4, 6, v138
	v_sub_u32_e32 v8, 0, v0
	s_and_b32 s61, s14, 0x3f00
	s_lshl_b32 s14, s59, 1
	v_bfe_u32 v7, v138, 2, 4
	v_xor_b32_e32 v2, v138, v8
	v_lshlrev_b32_e32 v9, 4, v4
	s_and_b32 s60, s14, 0xffffff80
	v_or_b32_e32 v3, v7, v9
	v_lshlrev_b32_e32 v2, 4, v2
	v_add_u32_e32 v0, s61, v3
	v_and_b32_e32 v134, 48, v2
	v_add_u32_e32 v2, s60, v3
	v_ashrrev_i32_e32 v1, 31, v0
	v_ashrrev_i32_e32 v3, 31, v2
	v_lshlrev_b64 v[0:1], 11, v[0:1]
	v_lshlrev_b64 v[2:3], 11, v[2:3]
	v_lshl_add_u64 v[0:1], s[30:31], 0, v[0:1]
	v_lshl_add_u64 v[2:3], s[8:9], 0, v[2:3]
	v_lshl_add_u64 v[0:1], v[0:1], 0, v[134:135]
	v_lshl_add_u64 v[2:3], v[2:3], 0, v[134:135]
	v_lshlrev_b32_e32 v134, 10, v4
	v_add_u32_e32 v10, 0x1000, v134
	v_readfirstlane_b32 s14, v134
	s_nop 0
	s_mov_b32 m0, s14
	v_readfirstlane_b32 s14, v10
	v_add_u32_e32 v10, 0x2000, v134
	v_lshl_add_u64 v[4:5], v[0:1], 0, s[96:97]
	s_mov_b32 m0, s14
	v_readfirstlane_b32 s14, v10
	v_add_u32_e32 v10, 0x3000, v134
	v_lshl_add_u64 v[4:5], v[0:1], 0, s[86:87]
	s_mov_b32 m0, s14
	s_mov_b64 s[12:13], 0x60000
	v_readfirstlane_b32 s14, v10
	v_lshl_add_u64 v[4:5], v[0:1], 0, s[12:13]
	s_mov_b32 m0, s14
	v_add_u32_e32 v10, 0x5000, v134
	v_add_u32_e32 v4, 0x4000, v134
	s_mov_b64 s[12:13], 0x20040
	v_readfirstlane_b32 s14, v4
	s_mov_b32 m0, s14
	v_readfirstlane_b32 s14, v10
	v_add_u32_e32 v10, 0x6000, v134
	v_lshl_add_u64 v[4:5], v[2:3], 0, s[96:97]
	s_mov_b32 m0, s14
	v_readfirstlane_b32 s14, v10
	v_add_u32_e32 v10, 0x7000, v134
	v_lshl_add_u64 v[4:5], v[0:1], 0, 64
	s_mov_b32 m0, s14
	v_readfirstlane_b32 s14, v10
	v_lshl_add_u64 v[4:5], v[0:1], 0, s[12:13]
	s_mov_b32 m0, s14
	s_mov_b64 s[14:15], 0x40040
	v_add_u32_e32 v10, 0x8000, v134
	v_lshl_add_u64 v[4:5], v[0:1], 0, s[14:15]
	v_readfirstlane_b32 s14, v10
	s_mov_b32 m0, s14
	s_mov_b64 s[14:15], 0x60040
	v_add_u32_e32 v4, 0x9000, v134
	v_lshl_add_u64 v[0:1], v[0:1], 0, s[14:15]
	v_readfirstlane_b32 s14, v4
	v_add_u32_e32 v4, 0xa000, v134
	s_mov_b32 m0, s14
	v_readfirstlane_b32 s14, v4
	v_lshl_add_u64 v[0:1], v[2:3], 0, 64
	s_mov_b32 m0, s14
	s_and_b32 s10, s4, 0xffffff80
	v_lshl_add_u64 v[0:1], v[2:3], 0, s[12:13]
	v_add_u32_e32 v2, 0xb000, v134
	s_and_b32 s11, s35, 0x3f00
	v_readfirstlane_b32 s14, v2
	s_mov_b32 m0, s14
	v_bitop3_b32 v2, v138, 3, v8 bitop3:0x48
	v_lshlrev_b32_e32 v0, 6, v138
	v_and_or_b32 v143, v0, s80, v6
	v_lshlrev_b32_e32 v0, 1, v138
	v_and_b32_e32 v1, 0x43, v138
	v_and_or_b32 v0, v0, 24, v1
	v_lshrrev_b32_e32 v1, 1, v138
	v_and_b32_e32 v1, 2, v1
	v_sub_u32_e32 v1, 0, v1
	v_bitop3_b32 v1, v1, v140, 2 bitop3:0x6c
	v_lshlrev_b32_e32 v1, 4, v1
	v_lshl_or_b32 v144, v0, 6, v1
	v_or_b32_e32 v0, 4, v0
	v_lshlrev_b32_e32 v1, 6, v0
	v_lshrrev_b32_e32 v0, 2, v0
	v_sub_u32_e32 v0, 0, v0
	v_bitop3_b32 v0, v0, v140, 3 bitop3:0x6c
	v_lshl_or_b32 v145, v0, 4, v1
	v_or_b32_e32 v0, s10, v7
	v_add_u32_e32 v0, v0, v9
	v_ashrrev_i32_e32 v1, 31, v0
	v_lshlrev_b64 v[0:1], 11, v[0:1]
	v_lshlrev_b32_e32 v2, 4, v2
	v_or_b32_e32 v0, v0, v2
	v_lshl_add_u64 v[128:129], s[8:9], 0, v[0:1]
	v_or_b32_e32 v0, s11, v7
	v_add_u32_e32 v0, v0, v9
	v_ashrrev_i32_e32 v1, 31, v0
	s_nop 0
	v_lshlrev_b64 v[0:1], 11, v[0:1]
	s_waitcnt lgkmcnt(0)
; #define WAIT_V(n) asm volatile("s_waitcnt vmcnt(%0)" ::"n"(n) : "memory")
; #define RAW_BARRIER() do { asm volatile("s_waitcnt lgkmcnt(0)" ::: "memory"); __builtin_amdgcn_s_barrier(); } while (0)
; #define DSR(dst, addr, off) asm volatile("ds_read_b128 %0, %1 offset:%2" : "=v"(dst) : "v"(addr), "n"(off) : "memory")
; __device__ __forceinline__ void gb_step(const u16* ga, const u16* gw, size_t a64, size_t w64, int ko, bool issue, ...
;     ...
;   const unsigned rdb = (unsigned)(size_t)(__attribute__((address_space(3))) const char*)rd;
;   const unsigned ab = rdb + (unsigned)(((wm * 128 + (lane & 15)) * GST + rsw) * 2);
;   const int wr0 = wn * 64 + (((lane & 15) >> 2) << 3) + (lane & 3);
;   const unsigned bb0 = rdb + (unsigned)((256 * GST + wr0 * GST + GSW(wr0, lane >> 4)) * 2);
;   const unsigned bb1 = rdb + (unsigned)((256 * GST + (wr0 + 4) * GST + GSW(wr0 + 4, lane >> 4)) * 2);
;   bf16x8 wf0, wf1, wf2, wf3, xf0, xf1, xf2, xf3, xf4, xf5, xf6, xf7;
;     ...
;   DSR(wf0, bb0, 0); DSR(wf1, bb1, 0); DSR(wf2, bb0, 2048); DSR(wf3, bb1, 2048);
;   DSR(xf0, ab, 0); DSR(xf1, ab, 1024); DSR(xf2, ab, 2048); DSR(xf3, ab, 3072);
;   DSR(xf4, ab, 4096); DSR(xf5, ab, 5120); DSR(xf6, ab, 6144); DSR(xf7, ab, 7168);
; template <class F>
; __device__ __forceinline__ void gemm_big(const ALbf& al, const u16* __restrict__ Wt, int K, int m0, int n0, const F& f, u16* sm) {
;     ...
;   f32x4 acc[4][8];
; #pragma unroll
;   for (int i = 0; i < 4; i++)
; #pragma unroll
;     for (int j = 0; j < 8; j++) acc[i][j] = (f32x4){0.f, 0.f, 0.f, 0.f};
;   const int srow = lane >> 2;
;   const int scol = ((lane & 3) ^ ((0 - (srow >> 2)) & 3)) * 8;
;   const u16* ga = al.A + (size_t)(m0 + wave * 16 + srow) * al.lda + scol;
;   const u16* gw = Wt + (size_t)(n0 + wave * 16 + srow) * K + scol;
;   const size_t a64 = (size_t)64 * al.lda, w64 = (size_t)64 * K;
;   const int nk = K >> 5;
;   WAIT_V(0);
;   gb_issue(ga, gw, a64, w64, 0, sm, wave);
;   gb_issue(ga, gw, a64, w64, 32, sm + GB_STAGE_EL, wave);
;   WAIT_V(6);
;   RAW_BARRIER();
	v_or_b32_e32 v0, v0, v2
	v_lshl_add_u64 v[130:131], s[30:31], 0, v[0:1]
	v_mov_b32_e32 v0, 0
	s_mov_b32 s93, 0
	s_mov_b64 s[10:11], 0
	s_mov_b32 s94, 0
	v_mov_b32_e32 v1, v0
	v_mov_b32_e32 v2, v0
	v_mov_b32_e32 v3, v0
	v_mov_b32_e32 v4, v0
	v_mov_b32_e32 v5, v0
	v_mov_b32_e32 v6, v0
	v_mov_b32_e32 v7, v0
	v_mov_b32_e32 v32, v0
	v_mov_b32_e32 v33, v0
	v_mov_b32_e32 v34, v0
	v_mov_b32_e32 v35, v0
	v_mov_b32_e32 v36, v0
	v_mov_b32_e32 v37, v0
	v_mov_b32_e32 v38, v0
	v_mov_b32_e32 v39, v0
	v_mov_b32_e32 v8, v0
	v_mov_b32_e32 v9, v0
	v_mov_b32_e32 v10, v0
	v_mov_b32_e32 v11, v0
	v_mov_b32_e32 v12, v0
	v_mov_b32_e32 v13, v0
	v_mov_b32_e32 v14, v0
	v_mov_b32_e32 v15, v0
	v_mov_b32_e32 v48, v0
	v_mov_b32_e32 v49, v0
	v_mov_b32_e32 v50, v0
	v_mov_b32_e32 v51, v0
	v_mov_b32_e32 v52, v0
	v_mov_b32_e32 v53, v0
	v_mov_b32_e32 v54, v0
	v_mov_b32_e32 v55, v0
	v_mov_b32_e32 v16, v0
	v_mov_b32_e32 v17, v0
	v_mov_b32_e32 v18, v0
	v_mov_b32_e32 v19, v0
	v_mov_b32_e32 v20, v0
	v_mov_b32_e32 v21, v0
	v_mov_b32_e32 v22, v0
	v_mov_b32_e32 v23, v0
	v_mov_b32_e32 v64, v0
	v_mov_b32_e32 v65, v0
	v_mov_b32_e32 v66, v0
	v_mov_b32_e32 v67, v0
	v_mov_b32_e32 v72, v0
	v_mov_b32_e32 v73, v0
	v_mov_b32_e32 v74, v0
	v_mov_b32_e32 v75, v0
	v_mov_b32_e32 v24, v0
	v_mov_b32_e32 v25, v0
	v_mov_b32_e32 v26, v0
	v_mov_b32_e32 v27, v0
	v_mov_b32_e32 v28, v0
	v_mov_b32_e32 v29, v0
	v_mov_b32_e32 v30, v0
	v_mov_b32_e32 v31, v0
	v_mov_b32_e32 v88, v0
	v_mov_b32_e32 v89, v0
	v_mov_b32_e32 v90, v0
	v_mov_b32_e32 v91, v0
	v_mov_b32_e32 v92, v0
	v_mov_b32_e32 v93, v0
	v_mov_b32_e32 v94, v0
	v_mov_b32_e32 v95, v0
	v_mov_b32_e32 v40, v0
	v_mov_b32_e32 v41, v0
	v_mov_b32_e32 v42, v0
	v_mov_b32_e32 v43, v0
	v_mov_b32_e32 v44, v0
	v_mov_b32_e32 v45, v0
	v_mov_b32_e32 v46, v0
	v_mov_b32_e32 v47, v0
	v_mov_b32_e32 v96, v0
	v_mov_b32_e32 v97, v0
	v_mov_b32_e32 v98, v0
	v_mov_b32_e32 v99, v0
	v_mov_b32_e32 v100, v0
	v_mov_b32_e32 v101, v0
	v_mov_b32_e32 v102, v0
	v_mov_b32_e32 v103, v0
	v_mov_b32_e32 v56, v0
	v_mov_b32_e32 v57, v0
	v_mov_b32_e32 v58, v0
	v_mov_b32_e32 v59, v0
	v_mov_b32_e32 v60, v0
	v_mov_b32_e32 v61, v0
	v_mov_b32_e32 v62, v0
	v_mov_b32_e32 v63, v0
	v_mov_b32_e32 v104, v0
	v_mov_b32_e32 v105, v0
	v_mov_b32_e32 v106, v0
	v_mov_b32_e32 v107, v0
	v_mov_b32_e32 v108, v0
	v_mov_b32_e32 v109, v0
	v_mov_b32_e32 v110, v0
	v_mov_b32_e32 v111, v0
	v_mov_b32_e32 v68, v0
	v_mov_b32_e32 v69, v0
	v_mov_b32_e32 v70, v0
	v_mov_b32_e32 v71, v0
	v_mov_b32_e32 v76, v0
	v_mov_b32_e32 v77, v0
	v_mov_b32_e32 v78, v0
	v_mov_b32_e32 v79, v0
	v_mov_b32_e32 v112, v0
	v_mov_b32_e32 v113, v0
	v_mov_b32_e32 v114, v0
	v_mov_b32_e32 v115, v0
	v_mov_b32_e32 v116, v0
	v_mov_b32_e32 v117, v0
	v_mov_b32_e32 v118, v0
	v_mov_b32_e32 v119, v0
	v_mov_b32_e32 v80, v0
	v_mov_b32_e32 v81, v0
	v_mov_b32_e32 v82, v0
	v_mov_b32_e32 v83, v0
	v_mov_b32_e32 v84, v0
	v_mov_b32_e32 v85, v0
	v_mov_b32_e32 v86, v0
	v_mov_b32_e32 v87, v0
	v_mov_b32_e32 v120, v0
	v_mov_b32_e32 v121, v0
	v_mov_b32_e32 v122, v0
	v_mov_b32_e32 v123, v0
	v_mov_b32_e32 v124, v0
	v_mov_b32_e32 v125, v0
	v_mov_b32_e32 v126, v0
	v_mov_b32_e32 v127, v0
	v_readfirstlane_b32 s10, v130
	v_readfirstlane_b32 s11, v131
	v_readfirstlane_b32 s14, v128
	v_readfirstlane_b32 s15, v129
	v_readfirstlane_b32 s94, v134
	v_and_b32_e32 v176, 63, v132
	v_lshrrev_b32_e32 v177, 6, v132
	v_lshrrev_b32_e32 v178, 3, v176
	v_and_b32_e32 v179, 7, v176
	v_lshrrev_b32_e32 v180, 4, v176
	v_and_b32_e32 v181, 1, v177
	v_lshrrev_b32_e32 v182, 1, v177
	v_lshl_add_u32 v183, v181, 2, v180
	v_xor_b32_e32 v183, v179, v183
	v_lshl_add_u32 v184, v177, 3, v178
	v_lshlrev_b32_e32 v188, 11, v184
	v_lshl_add_u32 v128, v183, 4, v188
	v_add_u32_e32 v129, 0x10000, v128
	v_add_u32_e32 v130, 0x40000, v128
	v_add_u32_e32 v131, 0x50000, v128
	v_bfe_u32 v185, v178, 1, 1
	v_lshl_or_b32 v185, v181, 1, v185
	v_lshl_or_b32 v185, v182, 2, v185
	v_xor_b32_e32 v185, v179, v185
	v_lshl_add_u32 v134, v185, 4, v188
	v_add_u32_e32 v143, 0x10000, v134
	v_add_u32_e32 v196, 0x20000, v134
	v_add_u32_e32 v197, 0x30000, v134
	v_and_b32_e32 v186, 15, v176
	v_bfe_u32 v187, v176, 1, 3
	v_xor_b32_e32 v187, v180, v187
	v_lshlrev_b32_e32 v187, 4, v187
	v_lshl_add_u32 v188, v182, 6, v186
	v_lshl_add_u32 v219, v188, 7, v187
	v_xor_b32_e32 v228, 64, v219
	v_lshrrev_b32_e32 v189, 2, v186
	v_lshlrev_b32_e32 v189, 3, v189
	v_and_b32_e32 v188, 3, v186
	v_add_u32_e32 v189, v189, v188
	v_lshl_add_u32 v189, v181, 6, v189
	v_lshl_add_u32 v231, v189, 7, v187
	v_xor_b32_e32 v216, 64, v231
	s_lshl_b32 s17, s94, 5
	s_sub_u32 s10, s10, s17
	s_subb_u32 s11, s11, 0
	s_sub_u32 s14, s14, s17
	s_subb_u32 s15, s15, 0
	s_add_u32 m0, s94, 0x8000
	s_nop 0
	global_load_lds_dwordx4 v128, s[10:11]
	s_add_u32 m0, s94, 0x9000
	s_nop 0
	global_load_lds_dwordx4 v129, s[10:11]
	s_add_u32 m0, s94, 0xa000
	s_nop 0
	global_load_lds_dwordx4 v130, s[10:11]
	s_add_u32 m0, s94, 0xb000
	s_nop 0
	global_load_lds_dwordx4 v131, s[10:11]
	s_add_u32 s10, s10, 0x20000
	s_addc_u32 s11, s11, 0
	s_add_u32 m0, s94, 0xc000
	s_nop 0
	global_load_lds_dwordx4 v128, s[10:11]
	s_add_u32 m0, s94, 0xd000
	s_nop 0
	global_load_lds_dwordx4 v129, s[10:11]
	s_add_u32 m0, s94, 0xe000
	s_nop 0
	global_load_lds_dwordx4 v130, s[10:11]
	s_add_u32 m0, s94, 0xf000
	s_nop 0
	global_load_lds_dwordx4 v131, s[10:11]
	s_add_u32 s10, s10, 0xfffe0080
	s_addc_u32 s11, s11, -1
	s_add_u32 m0, s94, 0x0
	s_nop 0
	global_load_lds_dwordx4 v134, s[14:15]
	s_add_u32 m0, s94, 0x1000
	s_nop 0
	global_load_lds_dwordx4 v143, s[14:15]
	s_add_u32 m0, s94, 0x2000
	s_nop 0
	global_load_lds_dwordx4 v196, s[14:15]
	s_add_u32 m0, s94, 0x3000
	s_nop 0
	global_load_lds_dwordx4 v197, s[14:15]
	s_add_u32 s14, s14, 0x80
	s_addc_u32 s15, s15, 0
	s_add_u32 m0, s94, 0x4000
	s_nop 0
	global_load_lds_dwordx4 v134, s[14:15]
	s_add_u32 m0, s94, 0x5000
	s_nop 0
	global_load_lds_dwordx4 v143, s[14:15]
	s_add_u32 m0, s94, 0x6000
	s_nop 0
	global_load_lds_dwordx4 v196, s[14:15]
	s_add_u32 m0, s94, 0x7000
	s_nop 0
	global_load_lds_dwordx4 v197, s[14:15]
	s_add_u32 s14, s14, 0x80
	s_addc_u32 s15, s15, 0
	s_waitcnt vmcnt(0)
	s_barrier
	s_mov_b32 s16, 0
	s_mov_b32 s93, 0
	ds_read_b128 v[144:147], v219 offset:32768
	ds_read_b128 v[148:151], v219 offset:34816
	ds_read_b128 v[152:155], v219 offset:36864
	ds_read_b128 v[156:159], v219 offset:38912
	ds_read_b128 v[160:163], v228 offset:32768
	ds_read_b128 v[164:167], v228 offset:34816
	ds_read_b128 v[168:171], v228 offset:36864
	ds_read_b128 v[172:175], v228 offset:38912
	v_add_u32_e32 v248, s16, v231
	ds_read_b128 v[236:239], v248 offset:0
	ds_read_b128 v[240:243], v248 offset:512
	ds_read_b128 v[244:247], v248 offset:4096
	ds_read_b128 v[248:251], v248 offset:4608
	s_waitcnt lgkmcnt(0)
	s_barrier

; __device__ __forceinline__ int ltid() { int t = threadIdx.x; asm volatile("" : "+v"(t)); return t; }
; #define WAIT_V(n) asm volatile("s_waitcnt vmcnt(%0)" ::"n"(n) : "memory")
; template <class F>
; __device__ __forceinline__ void gemm_big(const ALbf& al, const u16* __restrict__ Wt, int K, int m0, int n0, const F& f, u16* sm) {
;   const int tid = ltid(), lane = tid & 63, wave = tid >> 6;
;   const int wm = wave >> 1, wn = wave & 1;
;   const int rsw = GSW(lane & 15, lane >> 4);
;   f32x4 acc[4][8];
; #pragma unroll
;   for (int i = 0; i < 4; i++)
; #pragma unroll
;     for (int j = 0; j < 8; j++) acc[i][j] = (f32x4){0.f, 0.f, 0.f, 0.f};
;   const int srow = lane >> 2;
;   const int scol = ((lane & 3) ^ ((0 - (srow >> 2)) & 3)) * 8;
;   const u16* ga = al.A + (size_t)(m0 + wave * 16 + srow) * al.lda + scol;
;   const u16* gw = Wt + (size_t)(n0 + wave * 16 + srow) * K + scol;
;   const size_t a64 = (size_t)64 * al.lda, w64 = (size_t)64 * K;
;   const int nk = K >> 5;
;   WAIT_V(0);
;   gb_issue(ga, gw, a64, w64, 0, sm, wave);
.LBB0_521:
	v_mov_b32_e32 v138, v132
	s_lshl_b32 s8, s13, 8
	v_lshrrev_b32_e32 v0, 2, v138
	v_bfe_u32 v140, v138, 4, 2
	v_sub_u32_e32 v0, 0, v0
	v_bitop3_b32 v0, v140, v0, 3 bitop3:0x78
	v_lshlrev_b32_e32 v6, 4, v0
	v_lshrrev_b32_e32 v0, 4, v138
	v_ashrrev_i32_e32 v4, 6, v138
	v_sub_u32_e32 v8, 0, v0
	s_and_b32 s15, s8, 0x3f00
	s_lshl_b32 s8, s13, 1
	v_bfe_u32 v7, v138, 2, 4
	v_xor_b32_e32 v2, v138, v8
	v_lshlrev_b32_e32 v9, 4, v4
	s_load_dwordx16 s[60:75], s[0:1], 0x160
	s_and_b32 s14, s8, 0xffffff80
	v_or_b32_e32 v3, v7, v9
	v_lshlrev_b32_e32 v2, 4, v2
	v_add_u32_e32 v0, s15, v3
	v_and_b32_e32 v134, 48, v2
	v_add_u32_e32 v2, s14, v3
	v_ashrrev_i32_e32 v1, 31, v0
	v_ashrrev_i32_e32 v3, 31, v2
	v_lshlrev_b64 v[0:1], 11, v[0:1]
	v_lshlrev_b64 v[2:3], 11, v[2:3]
	s_waitcnt lgkmcnt(0)
	v_lshl_add_u64 v[0:1], s[30:31], 0, v[0:1]
	v_lshl_add_u64 v[2:3], s[74:75], 0, v[2:3]
	v_lshl_add_u64 v[0:1], v[0:1], 0, v[134:135]
	v_lshl_add_u64 v[2:3], v[2:3], 0, v[134:135]
	v_lshlrev_b32_e32 v134, 10, v4
	v_add_u32_e32 v10, 0x1000, v134
	v_readfirstlane_b32 s8, v134
	s_nop 0
	s_mov_b32 m0, s8
	v_readfirstlane_b32 s8, v10
	v_add_u32_e32 v10, 0x2000, v134
	v_lshl_add_u64 v[4:5], v[0:1], 0, s[96:97]
	s_mov_b32 m0, s8
	v_readfirstlane_b32 s8, v10
	v_lshl_add_u64 v[4:5], v[0:1], 0, s[86:87]
	s_mov_b32 m0, s8
	s_mov_b64 s[8:9], 0x60000
	v_add_u32_e32 v10, 0x3000, v134
	v_lshl_add_u64 v[4:5], v[0:1], 0, s[8:9]
	v_readfirstlane_b32 s8, v10
	s_mov_b32 m0, s8
	v_add_u32_e32 v10, 0x5000, v134
	v_add_u32_e32 v4, 0x4000, v134
	s_mov_b64 s[10:11], 0x20040
	v_readfirstlane_b32 s8, v4
	s_mov_b32 m0, s8
	v_readfirstlane_b32 s8, v10
	v_add_u32_e32 v10, 0x6000, v134
	v_lshl_add_u64 v[4:5], v[2:3], 0, s[96:97]
	s_mov_b32 m0, s8
	v_readfirstlane_b32 s8, v10
	v_add_u32_e32 v10, 0x7000, v134
	v_lshl_add_u64 v[4:5], v[0:1], 0, 64
	s_mov_b32 m0, s8
	v_readfirstlane_b32 s8, v10
	v_lshl_add_u64 v[4:5], v[0:1], 0, s[10:11]
	s_mov_b32 m0, s8
	s_mov_b64 s[8:9], 0x40040
	v_add_u32_e32 v10, 0x8000, v134
	v_lshl_add_u64 v[4:5], v[0:1], 0, s[8:9]
	v_readfirstlane_b32 s8, v10
	s_mov_b32 m0, s8
	s_mov_b64 s[8:9], 0x60040
	v_add_u32_e32 v4, 0x9000, v134
	v_lshl_add_u64 v[0:1], v[0:1], 0, s[8:9]
	v_readfirstlane_b32 s8, v4
	v_add_u32_e32 v4, 0xa000, v134
	s_mov_b32 m0, s8
	v_readfirstlane_b32 s8, v4
	v_lshl_add_u64 v[0:1], v[2:3], 0, 64
	s_mov_b32 m0, s8
	s_and_b32 s6, s4, 0xffffff80
	v_lshl_add_u64 v[0:1], v[2:3], 0, s[10:11]
	v_add_u32_e32 v2, 0xb000, v134
	s_and_b32 s7, s12, 0x3f00
	v_readfirstlane_b32 s8, v2
	s_mov_b32 m0, s8
	s_movk_i32 s8, 0xe3c0
	v_lshlrev_b32_e32 v0, 6, v138
	v_and_or_b32 v143, v0, s8, v6
	v_lshlrev_b32_e32 v0, 1, v138
	v_and_b32_e32 v1, 0x43, v138
	v_and_or_b32 v0, v0, 24, v1
	v_lshrrev_b32_e32 v1, 1, v138
	v_and_b32_e32 v1, 2, v1
	v_sub_u32_e32 v1, 0, v1
	v_bitop3_b32 v1, v1, v140, 2 bitop3:0x6c
	v_lshlrev_b32_e32 v1, 4, v1
	v_lshl_or_b32 v144, v0, 6, v1
	v_or_b32_e32 v0, 4, v0
	v_lshlrev_b32_e32 v1, 6, v0
	v_lshrrev_b32_e32 v0, 2, v0
	v_sub_u32_e32 v0, 0, v0
	v_bitop3_b32 v0, v0, v140, 3 bitop3:0x6c
	v_lshl_or_b32 v145, v0, 4, v1
	v_or_b32_e32 v0, s6, v7
	v_add_u32_e32 v0, v0, v9
	v_ashrrev_i32_e32 v1, 31, v0
	v_bitop3_b32 v2, v138, 3, v8 bitop3:0x48
	v_lshlrev_b64 v[0:1], 11, v[0:1]
	v_lshlrev_b32_e32 v2, 4, v2
	v_or_b32_e32 v0, v0, v2
	v_lshl_add_u64 v[128:129], s[74:75], 0, v[0:1]
	v_or_b32_e32 v0, s7, v7
	v_add_u32_e32 v0, v0, v9
	v_ashrrev_i32_e32 v1, 31, v0
	s_nop 0
	v_lshlrev_b64 v[0:1], 11, v[0:1]
	s_waitcnt lgkmcnt(0)
; __device__ __forceinline__ int ltid() { int t = threadIdx.x; asm volatile("" : "+v"(t)); return t; }
; #define WAIT_V(n) asm volatile("s_waitcnt vmcnt(%0)" ::"n"(n) : "memory")
; #define RAW_BARRIER() do { asm volatile("s_waitcnt lgkmcnt(0)" ::: "memory"); __builtin_amdgcn_s_barrier(); } while (0)
; template <class F>
; __device__ __forceinline__ void gemm_big(const ALbf& al, const u16* __restrict__ Wt, int K, int m0, int n0, const F& f, u16* sm) {
;   const int tid = ltid(), lane = tid & 63, wave = tid >> 6;
;   const int wm = wave >> 1, wn = wave & 1;
;   const int rsw = GSW(lane & 15, lane >> 4);
;   f32x4 acc[4][8];
; #pragma unroll
;   for (int i = 0; i < 4; i++)
; #pragma unroll
;     for (int j = 0; j < 8; j++) acc[i][j] = (f32x4){0.f, 0.f, 0.f, 0.f};
;   const int srow = lane >> 2;
;   const int scol = ((lane & 3) ^ ((0 - (srow >> 2)) & 3)) * 8;
;   const u16* ga = al.A + (size_t)(m0 + wave * 16 + srow) * al.lda + scol;
;   const u16* gw = Wt + (size_t)(n0 + wave * 16 + srow) * K + scol;
;   const size_t a64 = (size_t)64 * al.lda, w64 = (size_t)64 * K;
;   const int nk = K >> 5;
;   WAIT_V(0);
;   gb_issue(ga, gw, a64, w64, 0, sm, wave);
;   gb_issue(ga, gw, a64, w64, 32, sm + GB_STAGE_EL, wave);
;   WAIT_V(6);
;   RAW_BARRIER();
	v_or_b32_e32 v0, v0, v2
	v_lshl_add_u64 v[130:131], s[30:31], 0, v[0:1]
	v_mov_b32_e32 v0, 0
	s_mov_b32 s16, 0
	s_mov_b64 s[6:7], 0
	s_mov_b32 s17, 0
	v_mov_b32_e32 v1, v0
	v_mov_b32_e32 v2, v0
	v_mov_b32_e32 v3, v0
	v_mov_b32_e32 v4, v0
	v_mov_b32_e32 v5, v0
	v_mov_b32_e32 v6, v0
	v_mov_b32_e32 v7, v0
	v_mov_b32_e32 v32, v0
	v_mov_b32_e32 v33, v0
	v_mov_b32_e32 v34, v0
	v_mov_b32_e32 v35, v0
	v_mov_b32_e32 v36, v0
	v_mov_b32_e32 v37, v0
	v_mov_b32_e32 v38, v0
	v_mov_b32_e32 v39, v0
	v_mov_b32_e32 v8, v0
	v_mov_b32_e32 v9, v0
	v_mov_b32_e32 v10, v0
	v_mov_b32_e32 v11, v0
	v_mov_b32_e32 v12, v0
	v_mov_b32_e32 v13, v0
	v_mov_b32_e32 v14, v0
	v_mov_b32_e32 v15, v0
	v_mov_b32_e32 v48, v0
	v_mov_b32_e32 v49, v0
	v_mov_b32_e32 v50, v0
	v_mov_b32_e32 v51, v0
	v_mov_b32_e32 v52, v0
	v_mov_b32_e32 v53, v0
	v_mov_b32_e32 v54, v0
	v_mov_b32_e32 v55, v0
	v_mov_b32_e32 v16, v0
	v_mov_b32_e32 v17, v0
	v_mov_b32_e32 v18, v0
	v_mov_b32_e32 v19, v0
	v_mov_b32_e32 v20, v0
	v_mov_b32_e32 v21, v0
	v_mov_b32_e32 v22, v0
	v_mov_b32_e32 v23, v0
	v_mov_b32_e32 v64, v0
	v_mov_b32_e32 v65, v0
	v_mov_b32_e32 v66, v0
	v_mov_b32_e32 v67, v0
	v_mov_b32_e32 v68, v0
	v_mov_b32_e32 v69, v0
	v_mov_b32_e32 v70, v0
	v_mov_b32_e32 v71, v0
	v_mov_b32_e32 v24, v0
	v_mov_b32_e32 v25, v0
	v_mov_b32_e32 v26, v0
	v_mov_b32_e32 v27, v0
	v_mov_b32_e32 v28, v0
	v_mov_b32_e32 v29, v0
	v_mov_b32_e32 v30, v0
	v_mov_b32_e32 v31, v0
	v_mov_b32_e32 v80, v0
	v_mov_b32_e32 v81, v0
	v_mov_b32_e32 v82, v0
	v_mov_b32_e32 v83, v0
	v_mov_b32_e32 v84, v0
	v_mov_b32_e32 v85, v0
	v_mov_b32_e32 v86, v0
	v_mov_b32_e32 v87, v0
	v_mov_b32_e32 v40, v0
	v_mov_b32_e32 v41, v0
	v_mov_b32_e32 v42, v0
	v_mov_b32_e32 v43, v0
	v_mov_b32_e32 v44, v0
	v_mov_b32_e32 v45, v0
	v_mov_b32_e32 v46, v0
	v_mov_b32_e32 v47, v0
	v_mov_b32_e32 v96, v0
	v_mov_b32_e32 v97, v0
	v_mov_b32_e32 v98, v0
	v_mov_b32_e32 v99, v0
	v_mov_b32_e32 v100, v0
	v_mov_b32_e32 v101, v0
	v_mov_b32_e32 v102, v0
	v_mov_b32_e32 v103, v0
	v_mov_b32_e32 v56, v0
	v_mov_b32_e32 v57, v0
	v_mov_b32_e32 v58, v0
	v_mov_b32_e32 v59, v0
	v_mov_b32_e32 v60, v0
	v_mov_b32_e32 v61, v0
	v_mov_b32_e32 v62, v0
	v_mov_b32_e32 v63, v0
	v_mov_b32_e32 v104, v0
	v_mov_b32_e32 v105, v0
	v_mov_b32_e32 v106, v0
	v_mov_b32_e32 v107, v0
	v_mov_b32_e32 v108, v0
	v_mov_b32_e32 v109, v0
	v_mov_b32_e32 v110, v0
	v_mov_b32_e32 v111, v0
	v_mov_b32_e32 v72, v0
	v_mov_b32_e32 v73, v0
	v_mov_b32_e32 v74, v0
	v_mov_b32_e32 v75, v0
	v_mov_b32_e32 v76, v0
	v_mov_b32_e32 v77, v0
	v_mov_b32_e32 v78, v0
	v_mov_b32_e32 v79, v0
	v_mov_b32_e32 v112, v0
	v_mov_b32_e32 v113, v0
	v_mov_b32_e32 v114, v0
	v_mov_b32_e32 v115, v0
	v_mov_b32_e32 v116, v0
	v_mov_b32_e32 v117, v0
	v_mov_b32_e32 v118, v0
	v_mov_b32_e32 v119, v0
	v_mov_b32_e32 v88, v0
	v_mov_b32_e32 v89, v0
	v_mov_b32_e32 v90, v0
	v_mov_b32_e32 v91, v0
	v_mov_b32_e32 v92, v0
	v_mov_b32_e32 v93, v0
	v_mov_b32_e32 v94, v0
	v_mov_b32_e32 v95, v0
	v_mov_b32_e32 v120, v0
	v_mov_b32_e32 v121, v0
	v_mov_b32_e32 v122, v0
	v_mov_b32_e32 v123, v0
	v_mov_b32_e32 v124, v0
	v_mov_b32_e32 v125, v0
	v_mov_b32_e32 v126, v0
	v_mov_b32_e32 v127, v0
	v_readfirstlane_b32 s6, v130
	v_readfirstlane_b32 s7, v131
	v_readfirstlane_b32 s8, v128
	v_readfirstlane_b32 s9, v129
	v_readfirstlane_b32 s17, v134
	v_and_b32_e32 v176, 63, v132
	v_lshrrev_b32_e32 v177, 6, v132
	v_lshrrev_b32_e32 v178, 3, v176
	v_and_b32_e32 v179, 7, v176
	v_lshrrev_b32_e32 v180, 4, v176
	v_and_b32_e32 v181, 1, v177
	v_lshrrev_b32_e32 v182, 1, v177
	v_lshl_add_u32 v183, v181, 2, v180
	v_xor_b32_e32 v183, v179, v183
	v_lshl_add_u32 v184, v177, 3, v178
	v_lshlrev_b32_e32 v188, 11, v184
	v_lshl_add_u32 v128, v183, 4, v188
	v_add_u32_e32 v129, 0x10000, v128
	v_add_u32_e32 v130, 0x40000, v128
	v_add_u32_e32 v131, 0x50000, v128
	v_bfe_u32 v185, v178, 1, 1
	v_lshl_or_b32 v185, v181, 1, v185
	v_lshl_or_b32 v185, v182, 2, v185
	v_xor_b32_e32 v185, v179, v185
	v_lshl_add_u32 v134, v185, 4, v188
	v_add_u32_e32 v143, 0x10000, v134
	v_add_u32_e32 v196, 0x20000, v134
	v_add_u32_e32 v197, 0x30000, v134
	v_and_b32_e32 v186, 15, v176
	v_bfe_u32 v187, v176, 1, 3
	v_xor_b32_e32 v187, v180, v187
	v_lshlrev_b32_e32 v187, 4, v187
	v_lshl_add_u32 v188, v182, 6, v186
	v_lshl_add_u32 v219, v188, 7, v187
	v_xor_b32_e32 v228, 64, v219
	v_lshrrev_b32_e32 v189, 2, v186
	v_lshlrev_b32_e32 v189, 3, v189
	v_and_b32_e32 v188, 3, v186
	v_add_u32_e32 v189, v189, v188
	v_lshl_add_u32 v189, v181, 6, v189
	v_lshl_add_u32 v231, v189, 7, v187
	v_xor_b32_e32 v216, 64, v231
	s_lshl_b32 s11, s17, 5
	s_sub_u32 s6, s6, s11
	s_subb_u32 s7, s7, 0
	s_sub_u32 s8, s8, s11
	s_subb_u32 s9, s9, 0
	s_add_u32 m0, s17, 0x8000
	s_nop 0
	global_load_lds_dwordx4 v128, s[6:7]
	s_add_u32 m0, s17, 0x9000
	s_nop 0
	global_load_lds_dwordx4 v129, s[6:7]
	s_add_u32 m0, s17, 0xa000
	s_nop 0
	global_load_lds_dwordx4 v130, s[6:7]
	s_add_u32 m0, s17, 0xb000
	s_nop 0
	global_load_lds_dwordx4 v131, s[6:7]
	s_add_u32 s6, s6, 0x20000
	s_addc_u32 s7, s7, 0
	s_add_u32 m0, s17, 0xc000
	s_nop 0
	global_load_lds_dwordx4 v128, s[6:7]
	s_add_u32 m0, s17, 0xd000
	s_nop 0
	global_load_lds_dwordx4 v129, s[6:7]
	s_add_u32 m0, s17, 0xe000
	s_nop 0
	global_load_lds_dwordx4 v130, s[6:7]
	s_add_u32 m0, s17, 0xf000
	s_nop 0
	global_load_lds_dwordx4 v131, s[6:7]
	s_add_u32 s6, s6, 0xfffe0080
	s_addc_u32 s7, s7, -1
	s_add_u32 m0, s17, 0x0
	s_nop 0
	global_load_lds_dwordx4 v134, s[8:9]
	s_add_u32 m0, s17, 0x1000
	s_nop 0
	global_load_lds_dwordx4 v143, s[8:9]
	s_add_u32 m0, s17, 0x2000
	s_nop 0
	global_load_lds_dwordx4 v196, s[8:9]
	s_add_u32 m0, s17, 0x3000
	s_nop 0
	global_load_lds_dwordx4 v197, s[8:9]
	s_add_u32 s8, s8, 0x80
	s_addc_u32 s9, s9, 0
	s_add_u32 m0, s17, 0x4000
	s_nop 0
	global_load_lds_dwordx4 v134, s[8:9]
	s_add_u32 m0, s17, 0x5000
	s_nop 0
	global_load_lds_dwordx4 v143, s[8:9]
	s_add_u32 m0, s17, 0x6000
	s_nop 0
	global_load_lds_dwordx4 v196, s[8:9]
	s_add_u32 m0, s17, 0x7000
	s_nop 0
	global_load_lds_dwordx4 v197, s[8:9]
	s_add_u32 s8, s8, 0x80
	s_addc_u32 s9, s9, 0
	s_waitcnt vmcnt(0)
	s_barrier
	s_mov_b32 s10, 0
	s_mov_b32 s16, 0
	ds_read_b128 v[144:147], v219 offset:32768
	ds_read_b128 v[148:151], v219 offset:34816
	ds_read_b128 v[152:155], v219 offset:36864
	ds_read_b128 v[156:159], v219 offset:38912
	ds_read_b128 v[160:163], v228 offset:32768
	ds_read_b128 v[164:167], v228 offset:34816
	ds_read_b128 v[168:171], v228 offset:36864
	ds_read_b128 v[172:175], v228 offset:38912
	v_add_u32_e32 v248, s10, v231
	ds_read_b128 v[236:239], v248 offset:0
	ds_read_b128 v[240:243], v248 offset:512
	ds_read_b128 v[244:247], v248 offset:4096
	ds_read_b128 v[248:251], v248 offset:4608
	s_waitcnt lgkmcnt(0)
	s_barrier
